# EpiFfn and EpiGelu staging: eight rstd LDS reads hoisted into one batch (one wait instead of eight read-wait steps)
# speedup vs baseline: 1.0018x; 1.0018x over previous
; #define MFMA16(a, b, c) __builtin_amdgcn_mfma_f32_16x16x32_bf16((a), (b), (c), 0, 0, 0)
; DI bf16x8 ldfrag(const char* lds, int row, int chunk) { return *(const bf16x8*)(lds + swz(row, chunk)); }
; #define GEMM_SG1() do { __builtin_amdgcn_sched_group_barrier(0x100, 1, 0); __builtin_amdgcn_sched_group_barrier(0x008, 4, 0); } while (0)
; #define GEMM_SG2() do { __builtin_amdgcn_sched_group_barrier(0x100, 2, 0); __builtin_amdgcn_sched_group_barrier(0x008, 4, 0); } while (0)
; template <bool RSTD, bool SWAP>
; DI void gemm_tile(gacc_t& acc, const bf16_t* __restrict__ A, int lda, const bf16_t* __restrict__ Bt, int ldb, int K,
;                   char* lds, int tid, int wr, int wc, int lane, const float* ssq_row) {
;     ...
;     for (int kt = 0; kt < nk; ++kt) {
;         const char* cur = lds + (kt & 1) * 65536;
;         if (kt + 1 < nk) GEMM_ISSUE(kt + 1, (kt + 1) & 1);
;         bf16x8 bfr[2][4], afr[3];
; #pragma unroll
;         for (int n = 0; n < 4; ++n) bfr[0][n] = ldfrag(cur + 32768, wc * 64 + n * 16 + fr, fq);
;         afr[0] = ldfrag(cur, wr * 128 + fr, fq);
;         afr[1] = ldfrag(cur, wr * 128 + 16 + fr, fq);
; #pragma unroll
;         for (int idx = 0; idx < 16; ++idx) {
;             const int ks = idx >> 3, m = idx & 7;
;             if (idx < 14) afr[(idx + 2) % 3] = ldfrag(cur, wr * 128 + ((idx + 2) & 7) * 16 + fr, ((idx + 2) >> 3) * 4 + fq);
;             if (ks == 0 && m >= 2 && m < 6) bfr[1][m - 2] = ldfrag(cur + 32768, wc * 64 + (m - 2) * 16 + fr, 4 + fq);
; #pragma unroll
;             for (int n = 0; n < 4; ++n) acc[m][n] = SWAP ? MFMA16(bfr[ks][n], afr[idx % 3], acc[m][n]) : MFMA16(afr[idx % 3], bfr[ks][n], acc[m][n]);
;         }
;         __builtin_amdgcn_sched_group_barrier(0x100, 6, 0);
;     ...
;         GEMM_SG1(); GEMM_SG1(); GEMM_SG2(); GEMM_SG2(); GEMM_SG2(); GEMM_SG2(); GEMM_SG1(); GEMM_SG1();
;         GEMM_SG1(); GEMM_SG1(); GEMM_SG1(); GEMM_SG1(); GEMM_SG1(); GEMM_SG1();
;         __builtin_amdgcn_sched_group_barrier(0x008, 8, 0);
;         __builtin_amdgcn_sched_barrier(0);
;         asm volatile("s_waitcnt vmcnt(0)" ::: "memory");
;         __syncthreads();
;     }
.LBB0_373:
	s_and_b32 s20, s18, 0x10000
	v_lshl_add_u64 v[162:163], v[138:139], 0, s[6:7]
	s_add_i32 s20, s22, s20
	v_lshl_add_u64 v[164:165], v[136:137], 0, s[6:7]
	v_lshl_add_u64 v[166:167], v[162:163], 0, s[94:95]
	s_add_i32 s21, s20, 0x8000
	s_mov_b32 m0, s20
	v_lshl_add_u64 v[172:173], v[164:165], 0, s[14:15]
	global_load_lds_dwordx4 v[166:167], off
	v_mfma_f32_16x16x32_bf16 v[60:63], v[210:213], v[236:239], v[60:63]
	s_mov_b32 m0, s21
	v_lshl_add_u64 v[174:175], v[162:163], 0, s[96:97]
	global_load_lds_dwordx4 v[172:173], off
	v_mfma_f32_16x16x32_bf16 v[56:59], v[214:217], v[236:239], v[56:59]
	s_add_i32 m0, s20, 0x2000
	v_lshl_add_u64 v[176:177], v[164:165], 0, s[72:73]
	global_load_lds_dwordx4 v[174:175], off
	v_mfma_f32_16x16x32_bf16 v[52:55], v[218:221], v[236:239], v[52:55]
	s_add_i32 m0, s20, 0xa000
	v_lshl_add_u64 v[178:179], v[162:163], 0, s[80:81]
	global_load_lds_dwordx4 v[176:177], off
	v_mfma_f32_16x16x32_bf16 v[48:51], v[222:225], v[236:239], v[48:51]
	s_add_i32 m0, s20, 0x4000
	v_lshl_add_u64 v[180:181], v[164:165], 0, s[76:77]
	global_load_lds_dwordx4 v[178:179], off
	v_mfma_f32_16x16x32_bf16 v[44:47], v[210:213], v[240:243], v[44:47]
	s_add_i32 m0, s20, 0xc000
	v_lshl_add_u64 v[162:163], v[162:163], 0, s[82:83]
	global_load_lds_dwordx4 v[180:181], off
	v_mfma_f32_16x16x32_bf16 v[40:43], v[214:217], v[240:243], v[40:43]
	s_add_i32 m0, s20, 0x6000
	v_lshl_add_u64 v[164:165], v[164:165], 0, s[0:1]
	global_load_lds_dwordx4 v[162:163], off
	v_mfma_f32_16x16x32_bf16 v[36:39], v[218:221], v[240:243], v[36:39]
	s_add_i32 m0, s20, 0xe000
	s_add_i32 s19, s18, 0xffff0000
	global_load_lds_dwordx4 v[164:165], off
	v_mfma_f32_16x16x32_bf16 v[32:35], v[222:225], v[240:243], v[32:35]
	s_and_b32 s19, s19, 0x10000
	s_add_i32 s19, s19, 0
	v_add_u32_e32 v146, s19, v144
	v_add3_u32 v166, v146, v150, v151
	ds_read_b128 v[162:165], v166 offset:32768
	ds_read_b128 v[186:189], v166 offset:34816
	ds_read_b128 v[194:197], v166 offset:36864
	ds_read_b128 v[198:201], v166 offset:38912
	v_add_u32_e32 v167, v146, v148
	ds_read_b128 v[190:193], v167
	ds_read_b128 v[202:205], v167 offset:2048
	v_add_u32_e32 v166, v146, v152
	ds_read_b128 v[206:209], v167 offset:4096
	v_mfma_f32_16x16x32_bf16 v[28:31], v[210:213], v[244:247], v[28:31]
	v_mfma_f32_16x16x32_bf16 v[24:27], v[214:217], v[244:247], v[24:27]
	v_mfma_f32_16x16x32_bf16 v[20:23], v[218:221], v[244:247], v[20:23]
	v_mfma_f32_16x16x32_bf16 v[16:19], v[222:225], v[244:247], v[16:19]
	v_mfma_f32_16x16x32_bf16 v[12:15], v[210:213], v[248:251], v[12:15]
	v_mfma_f32_16x16x32_bf16 v[8:11], v[214:217], v[248:251], v[8:11]
	v_mfma_f32_16x16x32_bf16 v[4:7], v[218:221], v[248:251], v[4:7]
	v_mfma_f32_16x16x32_bf16 v[0:3], v[222:225], v[248:251], v[0:3]
	s_waitcnt lgkmcnt(2)
	v_mfma_f32_16x16x32_bf16 v[124:127], v[162:165], v[190:193], v[124:127]
	v_add_u32_e32 v146, v146, v154
	v_mfma_f32_16x16x32_bf16 v[120:123], v[186:189], v[190:193], v[120:123]
	v_mfma_f32_16x16x32_bf16 v[116:119], v[194:197], v[190:193], v[116:119]
	v_mfma_f32_16x16x32_bf16 v[112:115], v[198:201], v[190:193], v[112:115]
	ds_read_b128 v[190:193], v166
	v_add_u32_e32 v166, s19, v149
	v_add_u32_e32 v172, v166, v153
	s_waitcnt lgkmcnt(2)
	v_mfma_f32_16x16x32_bf16 v[108:111], v[162:165], v[202:205], v[108:111]
	v_mfma_f32_16x16x32_bf16 v[104:107], v[186:189], v[202:205], v[104:107]
	v_mfma_f32_16x16x32_bf16 v[100:103], v[194:197], v[202:205], v[100:103]
	v_mfma_f32_16x16x32_bf16 v[96:99], v[198:201], v[202:205], v[96:99]
	ds_read_b128 v[202:205], v167 offset:8192
	ds_read_b128 v[210:213], v172 offset:32768
	s_waitcnt lgkmcnt(3)
	v_mfma_f32_16x16x32_bf16 v[92:95], v[162:165], v[206:209], v[92:95]
	v_mfma_f32_16x16x32_bf16 v[88:91], v[186:189], v[206:209], v[88:91]
	v_mfma_f32_16x16x32_bf16 v[84:87], v[194:197], v[206:209], v[84:87]
	v_mfma_f32_16x16x32_bf16 v[80:83], v[198:201], v[206:209], v[80:83]
	ds_read_b128 v[206:209], v167 offset:10240
	ds_read_b128 v[214:217], v172 offset:34816
	s_waitcnt lgkmcnt(4)
	v_mfma_f32_16x16x32_bf16 v[76:79], v[162:165], v[190:193], v[76:79]
	v_mfma_f32_16x16x32_bf16 v[72:75], v[186:189], v[190:193], v[72:75]
	v_mfma_f32_16x16x32_bf16 v[68:71], v[194:197], v[190:193], v[68:71]
	v_mfma_f32_16x16x32_bf16 v[64:67], v[198:201], v[190:193], v[64:67]
	ds_read_b128 v[190:193], v167 offset:12288
	v_add_u32_e32 v167, v166, v155
	ds_read_b128 v[218:221], v172 offset:36864
	s_waitcnt lgkmcnt(5)
	v_mfma_f32_16x16x32_bf16 v[60:63], v[162:165], v[202:205], v[60:63]
	v_mfma_f32_16x16x32_bf16 v[56:59], v[186:189], v[202:205], v[56:59]
	v_mfma_f32_16x16x32_bf16 v[52:55], v[194:197], v[202:205], v[52:55]
	v_mfma_f32_16x16x32_bf16 v[48:51], v[198:201], v[202:205], v[48:51]
	ds_read_b128 v[222:225], v167 offset:38912
	ds_read_b128 v[202:205], v146
	v_add_u32_e32 v146, v166, v148
	s_waitcnt lgkmcnt(5)
	v_mfma_f32_16x16x32_bf16 v[44:47], v[162:165], v[206:209], v[44:47]
	v_add_u32_e32 v167, v166, v152
	v_mfma_f32_16x16x32_bf16 v[40:43], v[186:189], v[206:209], v[40:43]
	v_mfma_f32_16x16x32_bf16 v[36:39], v[194:197], v[206:209], v[36:39]
	v_mfma_f32_16x16x32_bf16 v[32:35], v[198:201], v[206:209], v[32:35]
	ds_read_b128 v[206:209], v146
	s_waitcnt lgkmcnt(4)
	v_mfma_f32_16x16x32_bf16 v[28:31], v[162:165], v[190:193], v[28:31]
	v_mfma_f32_16x16x32_bf16 v[24:27], v[186:189], v[190:193], v[24:27]
	v_mfma_f32_16x16x32_bf16 v[20:23], v[194:197], v[190:193], v[20:23]
	v_mfma_f32_16x16x32_bf16 v[16:19], v[198:201], v[190:193], v[16:19]
	ds_read_b128 v[190:193], v146 offset:2048
	s_waitcnt lgkmcnt(2)
; #define MFMA16(a, b, c) __builtin_amdgcn_mfma_f32_16x16x32_bf16((a), (b), (c), 0, 0, 0)
; DI bf16x8 ldfrag(const char* lds, int row, int chunk) { return *(const bf16x8*)(lds + swz(row, chunk)); }
; #define GEMM_SG1() do { __builtin_amdgcn_sched_group_barrier(0x100, 1, 0); __builtin_amdgcn_sched_group_barrier(0x008, 4, 0); } while (0)
; #define GEMM_SG2() do { __builtin_amdgcn_sched_group_barrier(0x100, 2, 0); __builtin_amdgcn_sched_group_barrier(0x008, 4, 0); } while (0)
; template <bool RSTD, bool SWAP>
; DI void gemm_tile(gacc_t& acc, const bf16_t* __restrict__ A, int lda, const bf16_t* __restrict__ Bt, int ldb, int K,
;                   char* lds, int tid, int wr, int wc, int lane, const float* ssq_row) {
;     ...
;         for (int idx = 0; idx < 16; ++idx) {
;             const int ks = idx >> 3, m = idx & 7;
;             if (idx < 14) afr[(idx + 2) % 3] = ldfrag(cur, wr * 128 + ((idx + 2) & 7) * 16 + fr, ((idx + 2) >> 3) * 4 + fq);
;             if (ks == 0 && m >= 2 && m < 6) bfr[1][m - 2] = ldfrag(cur + 32768, wc * 64 + (m - 2) * 16 + fr, 4 + fq);
; #pragma unroll
;             for (int n = 0; n < 4; ++n) acc[m][n] = SWAP ? MFMA16(bfr[ks][n], afr[idx % 3], acc[m][n]) : MFMA16(afr[idx % 3], bfr[ks][n], acc[m][n]);
;         }
;         __builtin_amdgcn_sched_group_barrier(0x100, 6, 0);
;     ...
;         GEMM_SG1(); GEMM_SG1(); GEMM_SG2(); GEMM_SG2(); GEMM_SG2(); GEMM_SG2(); GEMM_SG1(); GEMM_SG1();
;         GEMM_SG1(); GEMM_SG1(); GEMM_SG1(); GEMM_SG1(); GEMM_SG1(); GEMM_SG1();
;         __builtin_amdgcn_sched_group_barrier(0x008, 8, 0);
;         __builtin_amdgcn_sched_barrier(0);
;         asm volatile("s_waitcnt vmcnt(0)" ::: "memory");
;         __syncthreads();
;     }
	v_mfma_f32_16x16x32_bf16 v[12:15], v[162:165], v[202:205], v[12:15]
	v_mfma_f32_16x16x32_bf16 v[8:11], v[186:189], v[202:205], v[8:11]
	v_mfma_f32_16x16x32_bf16 v[4:7], v[194:197], v[202:205], v[4:7]
	v_mfma_f32_16x16x32_bf16 v[0:3], v[198:201], v[202:205], v[0:3]
	ds_read_b128 v[162:165], v146 offset:4096
	s_waitcnt lgkmcnt(2)
	v_mfma_f32_16x16x32_bf16 v[124:127], v[210:213], v[206:209], v[124:127]
	v_mfma_f32_16x16x32_bf16 v[120:123], v[214:217], v[206:209], v[120:123]
	v_mfma_f32_16x16x32_bf16 v[116:119], v[218:221], v[206:209], v[116:119]
	v_mfma_f32_16x16x32_bf16 v[112:115], v[222:225], v[206:209], v[112:115]
	ds_read_b128 v[186:189], v167
	s_waitcnt lgkmcnt(2)
	v_mfma_f32_16x16x32_bf16 v[108:111], v[210:213], v[190:193], v[108:111]
	v_mfma_f32_16x16x32_bf16 v[104:107], v[214:217], v[190:193], v[104:107]
	v_mfma_f32_16x16x32_bf16 v[100:103], v[218:221], v[190:193], v[100:103]
	v_mfma_f32_16x16x32_bf16 v[96:99], v[222:225], v[190:193], v[96:99]
	ds_read_b128 v[236:239], v146 offset:8192
	s_waitcnt lgkmcnt(2)
	v_mfma_f32_16x16x32_bf16 v[92:95], v[210:213], v[162:165], v[92:95]
	v_mfma_f32_16x16x32_bf16 v[88:91], v[214:217], v[162:165], v[88:91]
	v_mfma_f32_16x16x32_bf16 v[84:87], v[218:221], v[162:165], v[84:87]
	v_mfma_f32_16x16x32_bf16 v[80:83], v[222:225], v[162:165], v[80:83]
	ds_read_b128 v[240:243], v146 offset:10240
	ds_read_b128 v[244:247], v146 offset:12288
	v_add_u32_e32 v146, v166, v154
	ds_read_b128 v[248:251], v146
	s_waitcnt lgkmcnt(4)
	v_mfma_f32_16x16x32_bf16 v[76:79], v[210:213], v[186:189], v[76:79]
	v_mfma_f32_16x16x32_bf16 v[72:75], v[214:217], v[186:189], v[72:75]
	v_mfma_f32_16x16x32_bf16 v[68:71], v[218:221], v[186:189], v[68:71]
	v_mfma_f32_16x16x32_bf16 v[64:67], v[222:225], v[186:189], v[64:67]
	s_waitcnt lgkmcnt(0)
	s_waitcnt vmcnt(0)
	s_add_u32 s6, s6, 0x80
	s_addc_u32 s7, s7, 0
	s_add_i32 s18, s18, 0x10000
	s_cmpk_lg_i32 s6, 0x780
	s_waitcnt vmcnt(0)
	s_barrier
	s_cbranch_scc1 .LBB0_373
	v_mfma_f32_16x16x32_bf16 v[60:63], v[210:213], v[236:239], v[60:63]
	v_mfma_f32_16x16x32_bf16 v[56:59], v[214:217], v[236:239], v[56:59]
	v_mfma_f32_16x16x32_bf16 v[52:55], v[218:221], v[236:239], v[52:55]
	v_mfma_f32_16x16x32_bf16 v[48:51], v[222:225], v[236:239], v[48:51]
	v_mfma_f32_16x16x32_bf16 v[44:47], v[210:213], v[240:243], v[44:47]
	v_mfma_f32_16x16x32_bf16 v[40:43], v[214:217], v[240:243], v[40:43]
	v_mfma_f32_16x16x32_bf16 v[36:39], v[218:221], v[240:243], v[36:39]
	v_mfma_f32_16x16x32_bf16 v[32:35], v[222:225], v[240:243], v[32:35]
	v_mfma_f32_16x16x32_bf16 v[28:31], v[210:213], v[244:247], v[28:31]
	v_mfma_f32_16x16x32_bf16 v[24:27], v[214:217], v[244:247], v[24:27]
	v_mfma_f32_16x16x32_bf16 v[20:23], v[218:221], v[244:247], v[20:23]
	v_mfma_f32_16x16x32_bf16 v[16:19], v[222:225], v[244:247], v[16:19]
	v_mfma_f32_16x16x32_bf16 v[12:15], v[210:213], v[248:251], v[12:15]
	v_mfma_f32_16x16x32_bf16 v[8:11], v[214:217], v[248:251], v[8:11]
	v_mfma_f32_16x16x32_bf16 v[4:7], v[218:221], v[248:251], v[4:7]
	v_mfma_f32_16x16x32_bf16 v[0:3], v[222:225], v[248:251], v[0:3]
	ds_read_b128 v[136:139], v161
	ds_read_b128 v[162:165], v161 offset:2048
	ds_read_b128 v[190:193], v161 offset:4096
	ds_read_b128 v[194:197], v161 offset:6144
	v_add_u32_e32 v146, v156, v148
	ds_read_b128 v[186:189], v146
	ds_read_b128 v[198:201], v146 offset:2048
	v_add_u32_e32 v166, v156, v152
	ds_read_b128 v[202:205], v146 offset:4096
	s_waitcnt lgkmcnt(2)
	v_mfma_f32_16x16x32_bf16 v[124:127], v[136:139], v[186:189], v[124:127]
	s_sext_i32_i8 s6, s16
	v_mfma_f32_16x16x32_bf16 v[120:123], v[162:165], v[186:189], v[120:123]
	v_mfma_f32_16x16x32_bf16 v[116:119], v[190:193], v[186:189], v[116:119]
	v_mfma_f32_16x16x32_bf16 v[112:115], v[194:197], v[186:189], v[112:115]
	ds_read_b128 v[186:189], v166
	v_add_u32_e32 v166, v157, v153
	s_waitcnt lgkmcnt(2)
	v_mfma_f32_16x16x32_bf16 v[108:111], v[136:139], v[198:201], v[108:111]
	v_mfma_f32_16x16x32_bf16 v[104:107], v[162:165], v[198:201], v[104:107]
	v_mfma_f32_16x16x32_bf16 v[100:103], v[190:193], v[198:201], v[100:103]
	v_mfma_f32_16x16x32_bf16 v[96:99], v[194:197], v[198:201], v[96:99]
	ds_read_b128 v[198:201], v146 offset:8192
	ds_read_b128 v[206:209], v166
	s_waitcnt lgkmcnt(3)
	v_mfma_f32_16x16x32_bf16 v[92:95], v[136:139], v[202:205], v[92:95]
	v_mfma_f32_16x16x32_bf16 v[88:91], v[162:165], v[202:205], v[88:91]
	v_mfma_f32_16x16x32_bf16 v[84:87], v[190:193], v[202:205], v[84:87]
	v_mfma_f32_16x16x32_bf16 v[80:83], v[194:197], v[202:205], v[80:83]
	ds_read_b128 v[202:205], v146 offset:10240
	ds_read_b128 v[210:213], v166 offset:2048
	s_waitcnt lgkmcnt(4)
	v_mfma_f32_16x16x32_bf16 v[76:79], v[136:139], v[186:189], v[76:79]
	v_mfma_f32_16x16x32_bf16 v[72:75], v[162:165], v[186:189], v[72:75]
	v_mfma_f32_16x16x32_bf16 v[68:71], v[190:193], v[186:189], v[68:71]
	v_mfma_f32_16x16x32_bf16 v[64:67], v[194:197], v[186:189], v[64:67]
	ds_read_b128 v[186:189], v146 offset:12288
	v_add_u32_e32 v146, v156, v154
	ds_read_b128 v[214:217], v166 offset:4096
	s_waitcnt lgkmcnt(5)
	v_mfma_f32_16x16x32_bf16 v[60:63], v[136:139], v[198:201], v[60:63]
	v_mfma_f32_16x16x32_bf16 v[56:59], v[162:165], v[198:201], v[56:59]
	v_mfma_f32_16x16x32_bf16 v[52:55], v[190:193], v[198:201], v[52:55]
	v_mfma_f32_16x16x32_bf16 v[48:51], v[194:197], v[198:201], v[48:51]
	ds_read_b128 v[198:201], v146
	v_add_u32_e32 v146, v157, v155
	ds_read_b128 v[218:221], v146 offset:6144
	v_add_u32_e32 v146, v158, v148
	s_waitcnt lgkmcnt(5)
	v_mfma_f32_16x16x32_bf16 v[44:47], v[136:139], v[202:205], v[44:47]
	v_mfma_f32_16x16x32_bf16 v[40:43], v[162:165], v[202:205], v[40:43]
	v_mfma_f32_16x16x32_bf16 v[36:39], v[190:193], v[202:205], v[36:39]
	v_mfma_f32_16x16x32_bf16 v[32:35], v[194:197], v[202:205], v[32:35]
	ds_read_b128 v[202:205], v146
	s_waitcnt lgkmcnt(4)
; #define MFMA16(a, b, c) __builtin_amdgcn_mfma_f32_16x16x32_bf16((a), (b), (c), 0, 0, 0)
; template <bool RSTD, bool SWAP>
; DI void gemm_tile(gacc_t& acc, const bf16_t* __restrict__ A, int lda, const bf16_t* __restrict__ Bt, int ldb, int K,
;                   char* lds, int tid, int wr, int wc, int lane, const float* ssq_row) {
;     ...
;         for (int idx = 0; idx < 16; ++idx) {
;             const int ks = idx >> 3, m = idx & 7;
;             if (idx < 14) afr[(idx + 2) % 3] = ldfrag(cur, wr * 128 + ((idx + 2) & 7) * 16 + fr, ((idx + 2) >> 3) * 4 + fq);
;             if (ks == 0 && m >= 2 && m < 6) bfr[1][m - 2] = ldfrag(cur + 32768, wc * 64 + (m - 2) * 16 + fr, 4 + fq);
; #pragma unroll
;             for (int n = 0; n < 4; ++n) acc[m][n] = SWAP ? MFMA16(bfr[ks][n], afr[idx % 3], acc[m][n]) : MFMA16(afr[idx % 3], bfr[ks][n], acc[m][n]);
;         }
;         __builtin_amdgcn_sched_group_barrier(0x100, 6, 0);
;     ...
;         GEMM_SG1(); GEMM_SG1(); GEMM_SG2(); GEMM_SG2(); GEMM_SG2(); GEMM_SG2(); GEMM_SG1(); GEMM_SG1();
;         GEMM_SG1(); GEMM_SG1(); GEMM_SG1(); GEMM_SG1(); GEMM_SG1(); GEMM_SG1();
;         __builtin_amdgcn_sched_group_barrier(0x008, 8, 0);
;         __builtin_amdgcn_sched_barrier(0);
;         asm volatile("s_waitcnt vmcnt(0)" ::: "memory");
;         __syncthreads();
;     DI void operator()(gacc_t& acc, int pm, int pn, char* lds, int tid, int wr, int wc, int lane) const {
;         asm volatile("" : "+v"(tid), "+v"(lane));
;         const int fr = lane & 15, fq = lane >> 4;
;         char* lbase = lds + (wr * 128 + fr) * 528 + (wc * 64 + 4 * fq) * 2;
;         const float* rl = (const float*)(lds + RSTD_OFF) + wr * 128 + fr;
; #pragma unroll
;         for (int m = 0; m < 8; ++m) {
;             const float r = rl[m * 16];
; #pragma unroll
;             for (int n = 0; n < 4; ++n) {
;                 float g[4];
; #pragma unroll
;                 for (int j = 0; j < 4; ++j) {
;                     const float x = acc[m][n][j] * r;
;                     const float u = 0.7978845608028654f * (x + 0.044715f * x * x * x);
;                     const float e = __builtin_amdgcn_exp2f(-2.885390081777927f * u);
;                     g[j] = x * __builtin_amdgcn_rcpf(1.0f + e);
;                 }
;                 u32x2 w; w.x = pk2(g[0], g[1]); w.y = pk2(g[2], g[3]);
;                 *(u32x2*)(lbase + m * 16 * 528 + n * 32) = w;
	v_mfma_f32_16x16x32_bf16 v[28:31], v[136:139], v[186:189], v[28:31]
	v_mfma_f32_16x16x32_bf16 v[24:27], v[162:165], v[186:189], v[24:27]
	v_mfma_f32_16x16x32_bf16 v[20:23], v[190:193], v[186:189], v[20:23]
	v_mfma_f32_16x16x32_bf16 v[16:19], v[194:197], v[186:189], v[16:19]
	ds_read_b128 v[186:189], v146 offset:2048
	s_waitcnt lgkmcnt(3)
	v_mfma_f32_16x16x32_bf16 v[12:15], v[136:139], v[198:201], v[12:15]
	v_mfma_f32_16x16x32_bf16 v[8:11], v[162:165], v[198:201], v[8:11]
	v_mfma_f32_16x16x32_bf16 v[4:7], v[190:193], v[198:201], v[4:7]
	v_mfma_f32_16x16x32_bf16 v[0:3], v[194:197], v[198:201], v[0:3]
	ds_read_b128 v[136:139], v146 offset:4096
	s_waitcnt lgkmcnt(2)
	v_mfma_f32_16x16x32_bf16 v[162:165], v[206:209], v[202:205], v[124:127]
	s_nop 2
	v_add_u32_e32 v124, v158, v152
	v_mfma_f32_16x16x32_bf16 v[120:123], v[210:213], v[202:205], v[120:123]
	v_mfma_f32_16x16x32_bf16 v[116:119], v[214:217], v[202:205], v[116:119]
	v_mfma_f32_16x16x32_bf16 v[112:115], v[218:221], v[202:205], v[112:115]
	ds_read_b128 v[124:127], v124
	s_waitcnt lgkmcnt(2)
	v_mfma_f32_16x16x32_bf16 v[108:111], v[206:209], v[186:189], v[108:111]
	v_mfma_f32_16x16x32_bf16 v[104:107], v[210:213], v[186:189], v[104:107]
	v_mfma_f32_16x16x32_bf16 v[100:103], v[214:217], v[186:189], v[100:103]
	v_mfma_f32_16x16x32_bf16 v[96:99], v[218:221], v[186:189], v[96:99]
	ds_read_b128 v[186:189], v146 offset:8192
	s_waitcnt lgkmcnt(2)
	v_mfma_f32_16x16x32_bf16 v[92:95], v[206:209], v[136:139], v[92:95]
	v_mfma_f32_16x16x32_bf16 v[88:91], v[210:213], v[136:139], v[88:91]
	v_mfma_f32_16x16x32_bf16 v[84:87], v[214:217], v[136:139], v[84:87]
	v_mfma_f32_16x16x32_bf16 v[80:83], v[218:221], v[136:139], v[80:83]
	ds_read_b128 v[136:139], v146 offset:10240
	s_waitcnt lgkmcnt(2)
	v_mfma_f32_16x16x32_bf16 v[76:79], v[206:209], v[124:127], v[76:79]
	v_mfma_f32_16x16x32_bf16 v[72:75], v[210:213], v[124:127], v[72:75]
	v_mfma_f32_16x16x32_bf16 v[68:71], v[214:217], v[124:127], v[68:71]
	v_mfma_f32_16x16x32_bf16 v[64:67], v[218:221], v[124:127], v[64:67]
	ds_read_b128 v[124:127], v146 offset:12288
	v_add_u32_e32 v146, v158, v154
	s_waitcnt lgkmcnt(2)
	v_mfma_f32_16x16x32_bf16 v[60:63], v[206:209], v[186:189], v[60:63]
	v_mfma_f32_16x16x32_bf16 v[56:59], v[210:213], v[186:189], v[56:59]
	v_mfma_f32_16x16x32_bf16 v[52:55], v[214:217], v[186:189], v[52:55]
	v_mfma_f32_16x16x32_bf16 v[48:51], v[218:221], v[186:189], v[48:51]
	ds_read_b128 v[186:189], v146
	s_waitcnt lgkmcnt(2)
	v_mfma_f32_16x16x32_bf16 v[44:47], v[206:209], v[136:139], v[44:47]
	v_mfma_f32_16x16x32_bf16 v[40:43], v[210:213], v[136:139], v[40:43]
	v_mfma_f32_16x16x32_bf16 v[36:39], v[214:217], v[136:139], v[36:39]
	v_mfma_f32_16x16x32_bf16 v[32:35], v[218:221], v[136:139], v[32:35]
	s_waitcnt lgkmcnt(1)
	v_mfma_f32_16x16x32_bf16 v[28:31], v[206:209], v[124:127], v[28:31]
	v_mfma_f32_16x16x32_bf16 v[24:27], v[210:213], v[124:127], v[24:27]
	v_mfma_f32_16x16x32_bf16 v[20:23], v[214:217], v[124:127], v[20:23]
	v_mfma_f32_16x16x32_bf16 v[16:19], v[218:221], v[124:127], v[16:19]
	s_waitcnt lgkmcnt(0)
	v_mfma_f32_16x16x32_bf16 v[12:15], v[206:209], v[186:189], v[12:15]
	v_mfma_f32_16x16x32_bf16 v[8:11], v[210:213], v[186:189], v[8:11]
	v_mfma_f32_16x16x32_bf16 v[4:7], v[214:217], v[186:189], v[4:7]
	v_mfma_f32_16x16x32_bf16 v[0:3], v[218:221], v[186:189], v[0:3]
	v_mov_b32_e32 v124, v141
	v_mov_b32_e32 v125, v140
	s_waitcnt vmcnt(0)
	s_barrier
	s_nop 0
	v_and_b32_e32 v127, 15, v124
	v_or_b32_e32 v126, v127, v145
	v_ashrrev_i32_e32 v124, 1, v124
	v_mul_lo_u32 v126, v126, s3
	v_and_b32_e32 v124, -8, v124
	v_lshl_add_u32 v127, v127, 2, v160
	v_add3_u32 v126, v159, v126, v124
	ds_read_b32 v244, v127
	ds_read_b32 v245, v127 offset:64
	ds_read_b32 v246, v127 offset:128
	ds_read_b32 v247, v127 offset:192
	ds_read_b32 v248, v127 offset:256
	ds_read_b32 v249, v127 offset:320
	ds_read_b32 v250, v127 offset:384
	ds_read_b32 v251, v127 offset:448
	s_waitcnt lgkmcnt(0)
	v_mov_b32_e32 v124, v244
	v_pk_mul_f32 v[136:137], v[162:163], v[124:125] op_sel_hi:[1,0]
	s_nop 0
	v_mul_f32_e32 v138, 0x3d372713, v136
	v_mul_f32_e32 v139, 0x3d372713, v137
	v_mul_f32_e32 v138, v136, v138
	v_mul_f32_e32 v139, v137, v139
	v_fma_f32 v138, v136, v138, v136
	v_fma_f32 v139, v137, v139, v137
	v_mul_f32_e32 v138, 0x3f4c422a, v138
	v_mul_f32_e32 v139, 0x3f4c422a, v139
	v_mul_f32_e32 v138, 0xc038aa3b, v138
	v_mul_f32_e32 v139, 0xc038aa3b, v139
	v_exp_f32_e32 v138, v138
	v_exp_f32_e32 v139, v139
	v_pk_mul_f32 v[120:121], v[120:121], v[124:125] op_sel_hi:[1,0]
	v_pk_mul_f32 v[122:123], v[122:123], v[124:125] op_sel_hi:[1,0]
	v_add_f32_e32 v138, 1.0, v138
	v_add_f32_e32 v139, 1.0, v139
	v_rcp_f32_e32 v138, v138
	v_rcp_f32_e32 v139, v139
	v_pk_mul_f32 v[116:117], v[116:117], v[124:125] op_sel_hi:[1,0]
	v_pk_mul_f32 v[118:119], v[118:119], v[124:125] op_sel_hi:[1,0]
	v_pk_mul_f32 v[112:113], v[112:113], v[124:125] op_sel_hi:[1,0]
	v_pk_mul_f32 v[136:137], v[136:137], v[138:139]
	v_pk_mul_f32 v[138:139], v[164:165], v[124:125] op_sel_hi:[1,0]
	v_cvt_pk_bf16_f32 v136, v136, v137
	v_mul_f32_e32 v146, 0x3d372713, v138
	v_mul_f32_e32 v146, v138, v146
	v_fma_f32 v146, v138, v146, v138
	v_mul_f32_e32 v146, 0x3f4c422a, v146
	v_mul_f32_e32 v146, 0xc038aa3b, v146
	v_exp_f32_e32 v146, v146
	v_pk_mul_f32 v[114:115], v[114:115], v[124:125] op_sel_hi:[1,0]
	v_add_f32_e32 v146, 1.0, v146
	v_rcp_f32_e32 v162, v146
	v_mul_f32_e32 v146, 0x3d372713, v139
	v_mul_f32_e32 v146, v139, v146
	v_fma_f32 v146, v139, v146, v139
	v_mul_f32_e32 v146, 0x3f4c422a, v146
	v_mul_f32_e32 v146, 0xc038aa3b, v146
	v_exp_f32_e32 v146, v146
	s_nop 0
	v_add_f32_e32 v146, 1.0, v146
	v_rcp_f32_e32 v163, v146
	s_nop 0
; DI unsigned pk2(float a, float b) { f32x2 v = {a, b}; bf16x2_t r = __builtin_convertvector(v, bf16x2_t); return __builtin_bit_cast(unsigned, r); }
;     DI void operator()(gacc_t& acc, int pm, int pn, char* lds, int tid, int wr, int wc, int lane) const {
;     ...
;         for (int m = 0; m < 8; ++m) {
;             const float r = rl[m * 16];
; #pragma unroll
;             for (int n = 0; n < 4; ++n) {
;                 float g[4];
; #pragma unroll
;                 for (int j = 0; j < 4; ++j) {
;                     const float x = acc[m][n][j] * r;
;                     const float u = 0.7978845608028654f * (x + 0.044715f * x * x * x);
;                     const float e = __builtin_amdgcn_exp2f(-2.885390081777927f * u);
;                     g[j] = x * __builtin_amdgcn_rcpf(1.0f + e);
;                 }
;                 u32x2 w; w.x = pk2(g[0], g[1]); w.y = pk2(g[2], g[3]);
;                 *(u32x2*)(lbase + m * 16 * 528 + n * 32) = w;
;             }
;             __builtin_amdgcn_sched_barrier(0);
	v_pk_mul_f32 v[138:139], v[138:139], v[162:163]
	s_nop 0
	v_cvt_pk_bf16_f32 v137, v138, v139
	v_mul_f32_e32 v138, 0x3d372713, v120
	v_mul_f32_e32 v139, 0x3d372713, v121
	v_mul_f32_e32 v138, v120, v138
	v_mul_f32_e32 v139, v121, v139
	v_fma_f32 v138, v120, v138, v120
	v_fma_f32 v139, v121, v139, v121
	v_mul_f32_e32 v138, 0x3f4c422a, v138
	v_mul_f32_e32 v139, 0x3f4c422a, v139
	v_mul_f32_e32 v138, 0xc038aa3b, v138
	v_mul_f32_e32 v139, 0xc038aa3b, v139
	v_exp_f32_e32 v138, v138
	v_exp_f32_e32 v139, v139
	v_add_f32_e32 v138, 1.0, v138
	v_add_f32_e32 v139, 1.0, v139
	v_rcp_f32_e32 v138, v138
	v_rcp_f32_e32 v139, v139
	s_nop 0
	v_pk_mul_f32 v[120:121], v[120:121], v[138:139]
	v_mul_f32_e32 v138, 0x3d372713, v122
	v_mul_f32_e32 v139, 0x3d372713, v123
	v_mul_f32_e32 v138, v122, v138
	v_mul_f32_e32 v139, v123, v139
	v_fma_f32 v138, v122, v138, v122
	v_fma_f32 v139, v123, v139, v123
	v_mul_f32_e32 v138, 0x3f4c422a, v138
	v_mul_f32_e32 v139, 0x3f4c422a, v139
	v_mul_f32_e32 v138, 0xc038aa3b, v138
	v_mul_f32_e32 v139, 0xc038aa3b, v139
	v_exp_f32_e32 v138, v138
	v_exp_f32_e32 v139, v139
	v_cvt_pk_bf16_f32 v120, v120, v121
	v_add_f32_e32 v138, 1.0, v138
	v_add_f32_e32 v139, 1.0, v139
	v_rcp_f32_e32 v138, v138
	v_rcp_f32_e32 v139, v139
	s_nop 0
	v_pk_mul_f32 v[122:123], v[122:123], v[138:139]
	s_nop 0
	v_cvt_pk_bf16_f32 v121, v122, v123
	ds_write2_b64 v126, v[136:137], v[120:121] offset1:4
	v_mul_f32_e32 v120, 0x3d372713, v116
	v_mul_f32_e32 v121, 0x3d372713, v117
	v_mul_f32_e32 v120, v116, v120
	v_mul_f32_e32 v121, v117, v121
	v_fma_f32 v120, v116, v120, v116
	v_fma_f32 v121, v117, v121, v117
	v_mul_f32_e32 v120, 0x3f4c422a, v120
	v_mul_f32_e32 v121, 0x3f4c422a, v121
	v_mul_f32_e32 v120, 0xc038aa3b, v120
	v_mul_f32_e32 v121, 0xc038aa3b, v121
	v_exp_f32_e32 v120, v120
	v_exp_f32_e32 v121, v121
	v_add_f32_e32 v120, 1.0, v120
	v_add_f32_e32 v121, 1.0, v121
	v_rcp_f32_e32 v120, v120
	v_rcp_f32_e32 v121, v121
	s_nop 0
	v_pk_mul_f32 v[116:117], v[116:117], v[120:121]
	v_mul_f32_e32 v120, 0x3d372713, v118
	v_mul_f32_e32 v121, 0x3d372713, v119
	v_mul_f32_e32 v120, v118, v120
	v_mul_f32_e32 v121, v119, v121
	v_fma_f32 v120, v118, v120, v118
	v_fma_f32 v121, v119, v121, v119
	v_mul_f32_e32 v120, 0x3f4c422a, v120
	v_mul_f32_e32 v121, 0x3f4c422a, v121
	v_mul_f32_e32 v120, 0xc038aa3b, v120
	v_mul_f32_e32 v121, 0xc038aa3b, v121
	v_exp_f32_e32 v120, v120
	v_exp_f32_e32 v121, v121
	v_cvt_pk_bf16_f32 v116, v116, v117
	v_add_f32_e32 v120, 1.0, v120
	v_add_f32_e32 v121, 1.0, v121
	v_rcp_f32_e32 v120, v120
	v_rcp_f32_e32 v121, v121
	s_nop 0
	v_pk_mul_f32 v[118:119], v[118:119], v[120:121]
	s_nop 0
	v_cvt_pk_bf16_f32 v117, v118, v119
	v_mul_f32_e32 v118, 0x3d372713, v112
	v_mul_f32_e32 v119, 0x3d372713, v113
	v_mul_f32_e32 v118, v112, v118
	v_mul_f32_e32 v119, v113, v119
	v_fma_f32 v118, v112, v118, v112
	v_fma_f32 v119, v113, v119, v113
	v_mul_f32_e32 v118, 0x3f4c422a, v118
	v_mul_f32_e32 v119, 0x3f4c422a, v119
	v_mul_f32_e32 v118, 0xc038aa3b, v118
	v_mul_f32_e32 v119, 0xc038aa3b, v119
	v_exp_f32_e32 v118, v118
	v_exp_f32_e32 v119, v119
	v_add_f32_e32 v118, 1.0, v118
	v_add_f32_e32 v119, 1.0, v119
	v_rcp_f32_e32 v118, v118
	v_rcp_f32_e32 v119, v119
	s_nop 0
	v_pk_mul_f32 v[112:113], v[112:113], v[118:119]
	v_mul_f32_e32 v118, 0x3d372713, v114
	v_mul_f32_e32 v119, 0x3d372713, v115
	v_mul_f32_e32 v118, v114, v118
	v_mul_f32_e32 v119, v115, v119
	v_fma_f32 v118, v114, v118, v114
	v_fma_f32 v119, v115, v119, v115
	v_mul_f32_e32 v118, 0x3f4c422a, v118
	v_mul_f32_e32 v119, 0x3f4c422a, v119
	v_mul_f32_e32 v118, 0xc038aa3b, v118
	v_mul_f32_e32 v119, 0xc038aa3b, v119
	v_exp_f32_e32 v118, v118
	v_exp_f32_e32 v119, v119
	v_cvt_pk_bf16_f32 v112, v112, v113
	v_add_f32_e32 v118, 1.0, v118
	v_add_f32_e32 v119, 1.0, v119
	v_rcp_f32_e32 v118, v118
	v_rcp_f32_e32 v119, v119
	s_nop 0
	v_pk_mul_f32 v[114:115], v[114:115], v[118:119]
	s_nop 0
	v_cvt_pk_bf16_f32 v113, v114, v115
	ds_write2_b64 v126, v[116:117], v[112:113] offset0:8 offset1:12
	v_mov_b32_e32 v112, v245
	v_pk_mul_f32 v[108:109], v[108:109], v[112:113] op_sel_hi:[1,0]
	s_nop 0
	v_mul_f32_e32 v113, 0x3d372713, v108
	v_mul_f32_e32 v113, v108, v113
	v_fma_f32 v113, v108, v113, v108
	v_mul_f32_e32 v113, 0x3f4c422a, v113
	v_mul_f32_e32 v113, 0xc038aa3b, v113
	v_exp_f32_e32 v113, v113
	s_nop 0
	v_add_f32_e32 v113, 1.0, v113
	v_rcp_f32_e32 v114, v113
	v_mul_f32_e32 v113, 0x3d372713, v109
	v_mul_f32_e32 v113, v109, v113
	v_fma_f32 v113, v109, v113, v109
	v_mul_f32_e32 v113, 0x3f4c422a, v113
	v_mul_f32_e32 v113, 0xc038aa3b, v113
	v_exp_f32_e32 v113, v113
	s_nop 0
	v_add_f32_e32 v113, 1.0, v113
	v_pk_mul_f32 v[110:111], v[110:111], v[112:113] op_sel_hi:[1,0]
	v_rcp_f32_e32 v115, v113
	v_mul_f32_e32 v113, 0x3d372713, v110
	v_mul_f32_e32 v113, v110, v113
	v_fma_f32 v113, v110, v113, v110
	v_mul_f32_e32 v113, 0x3f4c422a, v113
	v_mul_f32_e32 v113, 0xc038aa3b, v113
	v_exp_f32_e32 v113, v113
	v_pk_mul_f32 v[108:109], v[108:109], v[114:115]
	v_add_f32_e32 v113, 1.0, v113
	v_rcp_f32_e32 v114, v113
	v_mul_f32_e32 v113, 0x3d372713, v111
	v_mul_f32_e32 v113, v111, v113
	v_fma_f32 v113, v111, v113, v111
	v_mul_f32_e32 v113, 0x3f4c422a, v113
	v_mul_f32_e32 v113, 0xc038aa3b, v113
	v_exp_f32_e32 v113, v113
	v_cvt_pk_bf16_f32 v108, v108, v109
	v_add_f32_e32 v113, 1.0, v113
	v_rcp_f32_e32 v115, v113
	v_pk_mul_f32 v[104:105], v[104:105], v[112:113] op_sel_hi:[1,0]
	v_pk_mul_f32 v[106:107], v[106:107], v[112:113] op_sel_hi:[1,0]
	v_pk_mul_f32 v[100:101], v[100:101], v[112:113] op_sel_hi:[1,0]
	v_pk_mul_f32 v[110:111], v[110:111], v[114:115]
	v_pk_mul_f32 v[102:103], v[102:103], v[112:113] op_sel_hi:[1,0]
	v_cvt_pk_bf16_f32 v109, v110, v111
; DI unsigned pk2(float a, float b) { f32x2 v = {a, b}; bf16x2_t r = __builtin_convertvector(v, bf16x2_t); return __builtin_bit_cast(unsigned, r); }
;     DI void operator()(gacc_t& acc, int pm, int pn, char* lds, int tid, int wr, int wc, int lane) const {
;     ...
;         for (int m = 0; m < 8; ++m) {
;             const float r = rl[m * 16];
; #pragma unroll
;             for (int n = 0; n < 4; ++n) {
;                 float g[4];
; #pragma unroll
;                 for (int j = 0; j < 4; ++j) {
;                     const float x = acc[m][n][j] * r;
;                     const float u = 0.7978845608028654f * (x + 0.044715f * x * x * x);
;                     const float e = __builtin_amdgcn_exp2f(-2.885390081777927f * u);
;                     g[j] = x * __builtin_amdgcn_rcpf(1.0f + e);
;                 }
;                 u32x2 w; w.x = pk2(g[0], g[1]); w.y = pk2(g[2], g[3]);
;                 *(u32x2*)(lbase + m * 16 * 528 + n * 32) = w;
;             }
;             __builtin_amdgcn_sched_barrier(0);
	v_mul_f32_e32 v110, 0x3d372713, v104
	v_mul_f32_e32 v111, 0x3d372713, v105
	v_mul_f32_e32 v110, v104, v110
	v_mul_f32_e32 v111, v105, v111
	v_fma_f32 v110, v104, v110, v104
	v_fma_f32 v111, v105, v111, v105
	v_mul_f32_e32 v110, 0x3f4c422a, v110
	v_mul_f32_e32 v111, 0x3f4c422a, v111
	v_mul_f32_e32 v110, 0xc038aa3b, v110
	v_mul_f32_e32 v111, 0xc038aa3b, v111
	v_exp_f32_e32 v110, v110
	v_exp_f32_e32 v111, v111
	v_pk_mul_f32 v[96:97], v[96:97], v[112:113] op_sel_hi:[1,0]
	v_pk_mul_f32 v[98:99], v[98:99], v[112:113] op_sel_hi:[1,0]
	v_add_f32_e32 v110, 1.0, v110
	v_add_f32_e32 v111, 1.0, v111
	v_rcp_f32_e32 v110, v110
	v_rcp_f32_e32 v111, v111
	s_nop 0
	v_pk_mul_f32 v[104:105], v[104:105], v[110:111]
	v_mul_f32_e32 v110, 0x3d372713, v106
	v_mul_f32_e32 v111, 0x3d372713, v107
	v_mul_f32_e32 v110, v106, v110
	v_mul_f32_e32 v111, v107, v111
	v_fma_f32 v110, v106, v110, v106
	v_fma_f32 v111, v107, v111, v107
	v_mul_f32_e32 v110, 0x3f4c422a, v110
	v_mul_f32_e32 v111, 0x3f4c422a, v111
	v_mul_f32_e32 v110, 0xc038aa3b, v110
	v_mul_f32_e32 v111, 0xc038aa3b, v111
	v_exp_f32_e32 v110, v110
	v_exp_f32_e32 v111, v111
	v_cvt_pk_bf16_f32 v104, v104, v105
	v_add_f32_e32 v110, 1.0, v110
	v_add_f32_e32 v111, 1.0, v111
	v_rcp_f32_e32 v110, v110
	v_rcp_f32_e32 v111, v111
	s_nop 0
	v_pk_mul_f32 v[106:107], v[106:107], v[110:111]
	s_nop 0
	v_cvt_pk_bf16_f32 v105, v106, v107
	v_add_u32_e32 v106, 0x2000, v126
	ds_write2_b64 v106, v[108:109], v[104:105] offset0:32 offset1:36
	v_mul_f32_e32 v104, 0x3d372713, v100
	v_mul_f32_e32 v105, 0x3d372713, v101
	v_mul_f32_e32 v104, v100, v104
	v_mul_f32_e32 v105, v101, v105
	v_fma_f32 v104, v100, v104, v100
	v_fma_f32 v105, v101, v105, v101
	v_mul_f32_e32 v104, 0x3f4c422a, v104
	v_mul_f32_e32 v105, 0x3f4c422a, v105
	v_mul_f32_e32 v104, 0xc038aa3b, v104
	v_mul_f32_e32 v105, 0xc038aa3b, v105
	v_exp_f32_e32 v104, v104
	v_exp_f32_e32 v105, v105
	v_add_f32_e32 v104, 1.0, v104
	v_add_f32_e32 v105, 1.0, v105
	v_rcp_f32_e32 v104, v104
	v_rcp_f32_e32 v105, v105
	s_nop 0
	v_pk_mul_f32 v[100:101], v[100:101], v[104:105]
	v_mul_f32_e32 v104, 0x3d372713, v102
	v_mul_f32_e32 v105, 0x3d372713, v103
	v_mul_f32_e32 v104, v102, v104
	v_mul_f32_e32 v105, v103, v105
	v_fma_f32 v104, v102, v104, v102
	v_fma_f32 v105, v103, v105, v103
	v_mul_f32_e32 v104, 0x3f4c422a, v104
	v_mul_f32_e32 v105, 0x3f4c422a, v105
	v_mul_f32_e32 v104, 0xc038aa3b, v104
	v_mul_f32_e32 v105, 0xc038aa3b, v105
	v_exp_f32_e32 v104, v104
	v_exp_f32_e32 v105, v105
	v_cvt_pk_bf16_f32 v100, v100, v101
	v_add_f32_e32 v104, 1.0, v104
	v_add_f32_e32 v105, 1.0, v105
	v_rcp_f32_e32 v104, v104
	v_rcp_f32_e32 v105, v105
	s_nop 0
	v_pk_mul_f32 v[102:103], v[102:103], v[104:105]
	s_nop 0
	v_cvt_pk_bf16_f32 v101, v102, v103
	v_mul_f32_e32 v102, 0x3d372713, v96
	v_mul_f32_e32 v103, 0x3d372713, v97
	v_mul_f32_e32 v102, v96, v102
	v_mul_f32_e32 v103, v97, v103
	v_fma_f32 v102, v96, v102, v96
	v_fma_f32 v103, v97, v103, v97
	v_mul_f32_e32 v102, 0x3f4c422a, v102
	v_mul_f32_e32 v103, 0x3f4c422a, v103
	v_mul_f32_e32 v102, 0xc038aa3b, v102
	v_mul_f32_e32 v103, 0xc038aa3b, v103
	v_exp_f32_e32 v102, v102
	v_exp_f32_e32 v103, v103
	v_add_f32_e32 v102, 1.0, v102
	v_add_f32_e32 v103, 1.0, v103
	v_rcp_f32_e32 v102, v102
	v_rcp_f32_e32 v103, v103
	s_nop 0
	v_pk_mul_f32 v[96:97], v[96:97], v[102:103]
	v_mul_f32_e32 v102, 0x3d372713, v98
	v_mul_f32_e32 v103, 0x3d372713, v99
	v_mul_f32_e32 v102, v98, v102
	v_mul_f32_e32 v103, v99, v103
	v_fma_f32 v102, v98, v102, v98
	v_fma_f32 v103, v99, v103, v99
	v_mul_f32_e32 v102, 0x3f4c422a, v102
	v_mul_f32_e32 v103, 0x3f4c422a, v103
	v_mul_f32_e32 v102, 0xc038aa3b, v102
	v_mul_f32_e32 v103, 0xc038aa3b, v103
	v_exp_f32_e32 v102, v102
	v_exp_f32_e32 v103, v103
	v_cvt_pk_bf16_f32 v96, v96, v97
	v_add_f32_e32 v102, 1.0, v102
	v_add_f32_e32 v103, 1.0, v103
	v_rcp_f32_e32 v102, v102
	v_rcp_f32_e32 v103, v103
	s_nop 0
	v_pk_mul_f32 v[98:99], v[98:99], v[102:103]
	s_nop 0
	v_cvt_pk_bf16_f32 v97, v98, v99
	ds_write2_b64 v106, v[100:101], v[96:97] offset0:40 offset1:44
	v_mov_b32_e32 v96, v246
	v_pk_mul_f32 v[92:93], v[92:93], v[96:97] op_sel_hi:[1,0]
	s_nop 0
	v_mul_f32_e32 v97, 0x3d372713, v92
	v_mul_f32_e32 v97, v92, v97
	v_fma_f32 v97, v92, v97, v92
	v_mul_f32_e32 v97, 0x3f4c422a, v97
	v_mul_f32_e32 v97, 0xc038aa3b, v97
	v_exp_f32_e32 v97, v97
	s_nop 0
	v_add_f32_e32 v97, 1.0, v97
	v_rcp_f32_e32 v98, v97
	v_mul_f32_e32 v97, 0x3d372713, v93
	v_mul_f32_e32 v97, v93, v97
	v_fma_f32 v97, v93, v97, v93
	v_mul_f32_e32 v97, 0x3f4c422a, v97
	v_mul_f32_e32 v97, 0xc038aa3b, v97
	v_exp_f32_e32 v97, v97
	s_nop 0
	v_add_f32_e32 v97, 1.0, v97
	v_pk_mul_f32 v[94:95], v[94:95], v[96:97] op_sel_hi:[1,0]
	v_rcp_f32_e32 v99, v97
	v_mul_f32_e32 v97, 0x3d372713, v94
	v_mul_f32_e32 v97, v94, v97
	v_fma_f32 v97, v94, v97, v94
	v_mul_f32_e32 v97, 0x3f4c422a, v97
	v_mul_f32_e32 v97, 0xc038aa3b, v97
	v_exp_f32_e32 v97, v97
	v_pk_mul_f32 v[92:93], v[92:93], v[98:99]
	v_add_f32_e32 v97, 1.0, v97
	v_rcp_f32_e32 v98, v97
	v_mul_f32_e32 v97, 0x3d372713, v95
	v_mul_f32_e32 v97, v95, v97
	v_fma_f32 v97, v95, v97, v95
	v_mul_f32_e32 v97, 0x3f4c422a, v97
	v_mul_f32_e32 v97, 0xc038aa3b, v97
	v_exp_f32_e32 v97, v97
	v_cvt_pk_bf16_f32 v92, v92, v93
	v_add_f32_e32 v97, 1.0, v97
	v_rcp_f32_e32 v99, v97
	v_pk_mul_f32 v[88:89], v[88:89], v[96:97] op_sel_hi:[1,0]
	v_pk_mul_f32 v[90:91], v[90:91], v[96:97] op_sel_hi:[1,0]
	v_pk_mul_f32 v[84:85], v[84:85], v[96:97] op_sel_hi:[1,0]
	v_pk_mul_f32 v[94:95], v[94:95], v[98:99]
	v_pk_mul_f32 v[86:87], v[86:87], v[96:97] op_sel_hi:[1,0]
	v_cvt_pk_bf16_f32 v93, v94, v95
	v_mul_f32_e32 v94, 0x3d372713, v88
	v_mul_f32_e32 v95, 0x3d372713, v89
	v_mul_f32_e32 v94, v88, v94
; DI unsigned pk2(float a, float b) { f32x2 v = {a, b}; bf16x2_t r = __builtin_convertvector(v, bf16x2_t); return __builtin_bit_cast(unsigned, r); }
;     DI void operator()(gacc_t& acc, int pm, int pn, char* lds, int tid, int wr, int wc, int lane) const {
;     ...
;         for (int m = 0; m < 8; ++m) {
;             const float r = rl[m * 16];
; #pragma unroll
;             for (int n = 0; n < 4; ++n) {
;                 float g[4];
; #pragma unroll
;                 for (int j = 0; j < 4; ++j) {
;                     const float x = acc[m][n][j] * r;
;                     const float u = 0.7978845608028654f * (x + 0.044715f * x * x * x);
;                     const float e = __builtin_amdgcn_exp2f(-2.885390081777927f * u);
;                     g[j] = x * __builtin_amdgcn_rcpf(1.0f + e);
;                 }
;                 u32x2 w; w.x = pk2(g[0], g[1]); w.y = pk2(g[2], g[3]);
;                 *(u32x2*)(lbase + m * 16 * 528 + n * 32) = w;
;             }
;             __builtin_amdgcn_sched_barrier(0);
	v_mul_f32_e32 v95, v89, v95
	v_fma_f32 v94, v88, v94, v88
	v_fma_f32 v95, v89, v95, v89
	v_mul_f32_e32 v94, 0x3f4c422a, v94
	v_mul_f32_e32 v95, 0x3f4c422a, v95
	v_mul_f32_e32 v94, 0xc038aa3b, v94
	v_mul_f32_e32 v95, 0xc038aa3b, v95
	v_exp_f32_e32 v94, v94
	v_exp_f32_e32 v95, v95
	v_pk_mul_f32 v[80:81], v[80:81], v[96:97] op_sel_hi:[1,0]
	v_pk_mul_f32 v[82:83], v[82:83], v[96:97] op_sel_hi:[1,0]
	v_add_f32_e32 v94, 1.0, v94
	v_add_f32_e32 v95, 1.0, v95
	v_rcp_f32_e32 v94, v94
	v_rcp_f32_e32 v95, v95
	s_nop 0
	v_pk_mul_f32 v[88:89], v[88:89], v[94:95]
	v_mul_f32_e32 v94, 0x3d372713, v90
	v_mul_f32_e32 v95, 0x3d372713, v91
	v_mul_f32_e32 v94, v90, v94
	v_mul_f32_e32 v95, v91, v95
	v_fma_f32 v94, v90, v94, v90
	v_fma_f32 v95, v91, v95, v91
	v_mul_f32_e32 v94, 0x3f4c422a, v94
	v_mul_f32_e32 v95, 0x3f4c422a, v95
	v_mul_f32_e32 v94, 0xc038aa3b, v94
	v_mul_f32_e32 v95, 0xc038aa3b, v95
	v_exp_f32_e32 v94, v94
	v_exp_f32_e32 v95, v95
	v_cvt_pk_bf16_f32 v88, v88, v89
	v_add_f32_e32 v94, 1.0, v94
	v_add_f32_e32 v95, 1.0, v95
	v_rcp_f32_e32 v94, v94
	v_rcp_f32_e32 v95, v95
	s_nop 0
	v_pk_mul_f32 v[90:91], v[90:91], v[94:95]
	s_nop 0
	v_cvt_pk_bf16_f32 v89, v90, v91
	v_add_u32_e32 v90, 0x4000, v126
	ds_write2_b64 v90, v[92:93], v[88:89] offset0:64 offset1:68
	v_mul_f32_e32 v88, 0x3d372713, v84
	v_mul_f32_e32 v89, 0x3d372713, v85
	v_mul_f32_e32 v88, v84, v88
	v_mul_f32_e32 v89, v85, v89
	v_fma_f32 v88, v84, v88, v84
	v_fma_f32 v89, v85, v89, v85
	v_mul_f32_e32 v88, 0x3f4c422a, v88
	v_mul_f32_e32 v89, 0x3f4c422a, v89
	v_mul_f32_e32 v88, 0xc038aa3b, v88
	v_mul_f32_e32 v89, 0xc038aa3b, v89
	v_exp_f32_e32 v88, v88
	v_exp_f32_e32 v89, v89
	v_add_f32_e32 v88, 1.0, v88
	v_add_f32_e32 v89, 1.0, v89
	v_rcp_f32_e32 v88, v88
	v_rcp_f32_e32 v89, v89
	s_nop 0
	v_pk_mul_f32 v[84:85], v[84:85], v[88:89]
	v_mul_f32_e32 v88, 0x3d372713, v86
	v_mul_f32_e32 v89, 0x3d372713, v87
	v_mul_f32_e32 v88, v86, v88
	v_mul_f32_e32 v89, v87, v89
	v_fma_f32 v88, v86, v88, v86
	v_fma_f32 v89, v87, v89, v87
	v_mul_f32_e32 v88, 0x3f4c422a, v88
	v_mul_f32_e32 v89, 0x3f4c422a, v89
	v_mul_f32_e32 v88, 0xc038aa3b, v88
	v_mul_f32_e32 v89, 0xc038aa3b, v89
	v_exp_f32_e32 v88, v88
	v_exp_f32_e32 v89, v89
	v_cvt_pk_bf16_f32 v84, v84, v85
	v_add_f32_e32 v88, 1.0, v88
	v_add_f32_e32 v89, 1.0, v89
	v_rcp_f32_e32 v88, v88
	v_rcp_f32_e32 v89, v89
	s_nop 0
	v_pk_mul_f32 v[86:87], v[86:87], v[88:89]
	s_nop 0
	v_cvt_pk_bf16_f32 v85, v86, v87
	v_mul_f32_e32 v86, 0x3d372713, v80
	v_mul_f32_e32 v87, 0x3d372713, v81
	v_mul_f32_e32 v86, v80, v86
	v_mul_f32_e32 v87, v81, v87
	v_fma_f32 v86, v80, v86, v80
	v_fma_f32 v87, v81, v87, v81
	v_mul_f32_e32 v86, 0x3f4c422a, v86
	v_mul_f32_e32 v87, 0x3f4c422a, v87
	v_mul_f32_e32 v86, 0xc038aa3b, v86
	v_mul_f32_e32 v87, 0xc038aa3b, v87
	v_exp_f32_e32 v86, v86
	v_exp_f32_e32 v87, v87
	v_add_f32_e32 v86, 1.0, v86
	v_add_f32_e32 v87, 1.0, v87
	v_rcp_f32_e32 v86, v86
	v_rcp_f32_e32 v87, v87
	s_nop 0
	v_pk_mul_f32 v[80:81], v[80:81], v[86:87]
	v_mul_f32_e32 v86, 0x3d372713, v82
	v_mul_f32_e32 v87, 0x3d372713, v83
	v_mul_f32_e32 v86, v82, v86
	v_mul_f32_e32 v87, v83, v87
	v_fma_f32 v86, v82, v86, v82
	v_fma_f32 v87, v83, v87, v83
	v_mul_f32_e32 v86, 0x3f4c422a, v86
	v_mul_f32_e32 v87, 0x3f4c422a, v87
	v_mul_f32_e32 v86, 0xc038aa3b, v86
	v_mul_f32_e32 v87, 0xc038aa3b, v87
	v_exp_f32_e32 v86, v86
	v_exp_f32_e32 v87, v87
	v_cvt_pk_bf16_f32 v80, v80, v81
	v_add_f32_e32 v86, 1.0, v86
	v_add_f32_e32 v87, 1.0, v87
	v_rcp_f32_e32 v86, v86
	v_rcp_f32_e32 v87, v87
	s_nop 0
	v_pk_mul_f32 v[82:83], v[82:83], v[86:87]
	s_nop 0
	v_cvt_pk_bf16_f32 v81, v82, v83
	ds_write2_b64 v90, v[84:85], v[80:81] offset0:72 offset1:76
	v_mov_b32_e32 v80, v247
	v_pk_mul_f32 v[76:77], v[76:77], v[80:81] op_sel_hi:[1,0]
	s_nop 0
	v_mul_f32_e32 v81, 0x3d372713, v76
	v_mul_f32_e32 v81, v76, v81
	v_fma_f32 v81, v76, v81, v76
	v_mul_f32_e32 v81, 0x3f4c422a, v81
	v_mul_f32_e32 v81, 0xc038aa3b, v81
	v_exp_f32_e32 v81, v81
	s_nop 0
	v_add_f32_e32 v81, 1.0, v81
	v_rcp_f32_e32 v82, v81
	v_mul_f32_e32 v81, 0x3d372713, v77
	v_mul_f32_e32 v81, v77, v81
	v_fma_f32 v81, v77, v81, v77
	v_mul_f32_e32 v81, 0x3f4c422a, v81
	v_mul_f32_e32 v81, 0xc038aa3b, v81
	v_exp_f32_e32 v81, v81
	s_nop 0
	v_add_f32_e32 v81, 1.0, v81
	v_pk_mul_f32 v[78:79], v[78:79], v[80:81] op_sel_hi:[1,0]
	v_rcp_f32_e32 v83, v81
	v_mul_f32_e32 v81, 0x3d372713, v78
	v_mul_f32_e32 v81, v78, v81
	v_fma_f32 v81, v78, v81, v78
	v_mul_f32_e32 v81, 0x3f4c422a, v81
	v_mul_f32_e32 v81, 0xc038aa3b, v81
	v_exp_f32_e32 v81, v81
	v_pk_mul_f32 v[76:77], v[76:77], v[82:83]
	v_add_f32_e32 v81, 1.0, v81
	v_rcp_f32_e32 v82, v81
	v_mul_f32_e32 v81, 0x3d372713, v79
	v_mul_f32_e32 v81, v79, v81
	v_fma_f32 v81, v79, v81, v79
	v_mul_f32_e32 v81, 0x3f4c422a, v81
	v_mul_f32_e32 v81, 0xc038aa3b, v81
	v_exp_f32_e32 v81, v81
	v_cvt_pk_bf16_f32 v76, v76, v77
	v_add_f32_e32 v81, 1.0, v81
	v_rcp_f32_e32 v83, v81
	v_pk_mul_f32 v[72:73], v[72:73], v[80:81] op_sel_hi:[1,0]
	v_pk_mul_f32 v[74:75], v[74:75], v[80:81] op_sel_hi:[1,0]
	v_pk_mul_f32 v[68:69], v[68:69], v[80:81] op_sel_hi:[1,0]
	v_pk_mul_f32 v[78:79], v[78:79], v[82:83]
	v_pk_mul_f32 v[70:71], v[70:71], v[80:81] op_sel_hi:[1,0]
	v_cvt_pk_bf16_f32 v77, v78, v79
	v_mul_f32_e32 v78, 0x3d372713, v72
	v_mul_f32_e32 v79, 0x3d372713, v73
	v_mul_f32_e32 v78, v72, v78
	v_mul_f32_e32 v79, v73, v79
	v_fma_f32 v78, v72, v78, v72
	v_fma_f32 v79, v73, v79, v73
	v_mul_f32_e32 v78, 0x3f4c422a, v78
	v_mul_f32_e32 v79, 0x3f4c422a, v79
	v_mul_f32_e32 v78, 0xc038aa3b, v78
	v_mul_f32_e32 v79, 0xc038aa3b, v79
	v_exp_f32_e32 v78, v78
	v_exp_f32_e32 v79, v79
	v_pk_mul_f32 v[64:65], v[64:65], v[80:81] op_sel_hi:[1,0]
; DI unsigned pk2(float a, float b) { f32x2 v = {a, b}; bf16x2_t r = __builtin_convertvector(v, bf16x2_t); return __builtin_bit_cast(unsigned, r); }
;     DI void operator()(gacc_t& acc, int pm, int pn, char* lds, int tid, int wr, int wc, int lane) const {
;     ...
;         for (int m = 0; m < 8; ++m) {
;             const float r = rl[m * 16];
; #pragma unroll
;             for (int n = 0; n < 4; ++n) {
;                 float g[4];
; #pragma unroll
;                 for (int j = 0; j < 4; ++j) {
;                     const float x = acc[m][n][j] * r;
;                     const float u = 0.7978845608028654f * (x + 0.044715f * x * x * x);
;                     const float e = __builtin_amdgcn_exp2f(-2.885390081777927f * u);
;                     g[j] = x * __builtin_amdgcn_rcpf(1.0f + e);
;                 }
;                 u32x2 w; w.x = pk2(g[0], g[1]); w.y = pk2(g[2], g[3]);
;                 *(u32x2*)(lbase + m * 16 * 528 + n * 32) = w;
;             }
;             __builtin_amdgcn_sched_barrier(0);
	v_pk_mul_f32 v[66:67], v[66:67], v[80:81] op_sel_hi:[1,0]
	v_add_f32_e32 v78, 1.0, v78
	v_add_f32_e32 v79, 1.0, v79
	v_rcp_f32_e32 v78, v78
	v_rcp_f32_e32 v79, v79
	s_nop 0
	v_pk_mul_f32 v[72:73], v[72:73], v[78:79]
	v_mul_f32_e32 v78, 0x3d372713, v74
	v_mul_f32_e32 v79, 0x3d372713, v75
	v_mul_f32_e32 v78, v74, v78
	v_mul_f32_e32 v79, v75, v79
	v_fma_f32 v78, v74, v78, v74
	v_fma_f32 v79, v75, v79, v75
	v_mul_f32_e32 v78, 0x3f4c422a, v78
	v_mul_f32_e32 v79, 0x3f4c422a, v79
	v_mul_f32_e32 v78, 0xc038aa3b, v78
	v_mul_f32_e32 v79, 0xc038aa3b, v79
	v_exp_f32_e32 v78, v78
	v_exp_f32_e32 v79, v79
	v_cvt_pk_bf16_f32 v72, v72, v73
	v_add_f32_e32 v78, 1.0, v78
	v_add_f32_e32 v79, 1.0, v79
	v_rcp_f32_e32 v78, v78
	v_rcp_f32_e32 v79, v79
	s_nop 0
	v_pk_mul_f32 v[74:75], v[74:75], v[78:79]
	s_nop 0
	v_cvt_pk_bf16_f32 v73, v74, v75
	v_add_u32_e32 v74, 0x6000, v126
	ds_write2_b64 v74, v[76:77], v[72:73] offset0:96 offset1:100
	v_mul_f32_e32 v72, 0x3d372713, v68
	v_mul_f32_e32 v73, 0x3d372713, v69
	v_mul_f32_e32 v72, v68, v72
	v_mul_f32_e32 v73, v69, v73
	v_fma_f32 v72, v68, v72, v68
	v_fma_f32 v73, v69, v73, v69
	v_mul_f32_e32 v72, 0x3f4c422a, v72
	v_mul_f32_e32 v73, 0x3f4c422a, v73
	v_mul_f32_e32 v72, 0xc038aa3b, v72
	v_mul_f32_e32 v73, 0xc038aa3b, v73
	v_exp_f32_e32 v72, v72
	v_exp_f32_e32 v73, v73
	v_add_f32_e32 v72, 1.0, v72
	v_add_f32_e32 v73, 1.0, v73
	v_rcp_f32_e32 v72, v72
	v_rcp_f32_e32 v73, v73
	s_nop 0
	v_pk_mul_f32 v[68:69], v[68:69], v[72:73]
	v_mul_f32_e32 v72, 0x3d372713, v70
	v_mul_f32_e32 v73, 0x3d372713, v71
	v_mul_f32_e32 v72, v70, v72
	v_mul_f32_e32 v73, v71, v73
	v_fma_f32 v72, v70, v72, v70
	v_fma_f32 v73, v71, v73, v71
	v_mul_f32_e32 v72, 0x3f4c422a, v72
	v_mul_f32_e32 v73, 0x3f4c422a, v73
	v_mul_f32_e32 v72, 0xc038aa3b, v72
	v_mul_f32_e32 v73, 0xc038aa3b, v73
	v_exp_f32_e32 v72, v72
	v_exp_f32_e32 v73, v73
	v_cvt_pk_bf16_f32 v68, v68, v69
	v_add_f32_e32 v72, 1.0, v72
	v_add_f32_e32 v73, 1.0, v73
	v_rcp_f32_e32 v72, v72
	v_rcp_f32_e32 v73, v73
	s_nop 0
	v_pk_mul_f32 v[70:71], v[70:71], v[72:73]
	s_nop 0
	v_cvt_pk_bf16_f32 v69, v70, v71
	v_mul_f32_e32 v70, 0x3d372713, v64
	v_mul_f32_e32 v71, 0x3d372713, v65
	v_mul_f32_e32 v70, v64, v70
	v_mul_f32_e32 v71, v65, v71
	v_fma_f32 v70, v64, v70, v64
	v_fma_f32 v71, v65, v71, v65
	v_mul_f32_e32 v70, 0x3f4c422a, v70
	v_mul_f32_e32 v71, 0x3f4c422a, v71
	v_mul_f32_e32 v70, 0xc038aa3b, v70
	v_mul_f32_e32 v71, 0xc038aa3b, v71
	v_exp_f32_e32 v70, v70
	v_exp_f32_e32 v71, v71
	v_add_f32_e32 v70, 1.0, v70
	v_add_f32_e32 v71, 1.0, v71
	v_rcp_f32_e32 v70, v70
	v_rcp_f32_e32 v71, v71
	s_nop 0
	v_pk_mul_f32 v[64:65], v[64:65], v[70:71]
	v_mul_f32_e32 v70, 0x3d372713, v66
	v_mul_f32_e32 v71, 0x3d372713, v67
	v_mul_f32_e32 v70, v66, v70
	v_mul_f32_e32 v71, v67, v71
	v_fma_f32 v70, v66, v70, v66
	v_fma_f32 v71, v67, v71, v67
	v_mul_f32_e32 v70, 0x3f4c422a, v70
	v_mul_f32_e32 v71, 0x3f4c422a, v71
	v_mul_f32_e32 v70, 0xc038aa3b, v70
	v_mul_f32_e32 v71, 0xc038aa3b, v71
	v_exp_f32_e32 v70, v70
	v_exp_f32_e32 v71, v71
	v_cvt_pk_bf16_f32 v64, v64, v65
	v_add_f32_e32 v70, 1.0, v70
	v_add_f32_e32 v71, 1.0, v71
	v_rcp_f32_e32 v70, v70
	v_rcp_f32_e32 v71, v71
	s_nop 0
	v_pk_mul_f32 v[66:67], v[66:67], v[70:71]
	s_nop 0
	v_cvt_pk_bf16_f32 v65, v66, v67
	ds_write2_b64 v74, v[68:69], v[64:65] offset0:104 offset1:108
	v_mov_b32_e32 v64, v248
	v_pk_mul_f32 v[60:61], v[60:61], v[64:65] op_sel_hi:[1,0]
	s_nop 0
	v_mul_f32_e32 v65, 0x3d372713, v60
	v_mul_f32_e32 v65, v60, v65
	v_fma_f32 v65, v60, v65, v60
	v_mul_f32_e32 v65, 0x3f4c422a, v65
	v_mul_f32_e32 v65, 0xc038aa3b, v65
	v_exp_f32_e32 v65, v65
	s_nop 0
	v_add_f32_e32 v65, 1.0, v65
	v_rcp_f32_e32 v66, v65
	v_mul_f32_e32 v65, 0x3d372713, v61
	v_mul_f32_e32 v65, v61, v65
	v_fma_f32 v65, v61, v65, v61
	v_mul_f32_e32 v65, 0x3f4c422a, v65
	v_mul_f32_e32 v65, 0xc038aa3b, v65
	v_exp_f32_e32 v65, v65
	s_nop 0
	v_add_f32_e32 v65, 1.0, v65
	v_pk_mul_f32 v[62:63], v[62:63], v[64:65] op_sel_hi:[1,0]
	v_rcp_f32_e32 v67, v65
	v_mul_f32_e32 v65, 0x3d372713, v62
	v_mul_f32_e32 v65, v62, v65
	v_fma_f32 v65, v62, v65, v62
	v_mul_f32_e32 v65, 0x3f4c422a, v65
	v_mul_f32_e32 v65, 0xc038aa3b, v65
	v_exp_f32_e32 v65, v65
	v_pk_mul_f32 v[60:61], v[60:61], v[66:67]
	v_add_f32_e32 v65, 1.0, v65
	v_rcp_f32_e32 v66, v65
	v_mul_f32_e32 v65, 0x3d372713, v63
	v_mul_f32_e32 v65, v63, v65
	v_fma_f32 v65, v63, v65, v63
	v_mul_f32_e32 v65, 0x3f4c422a, v65
	v_mul_f32_e32 v65, 0xc038aa3b, v65
	v_exp_f32_e32 v65, v65
	v_cvt_pk_bf16_f32 v60, v60, v61
	v_add_f32_e32 v65, 1.0, v65
	v_rcp_f32_e32 v67, v65
	v_pk_mul_f32 v[56:57], v[56:57], v[64:65] op_sel_hi:[1,0]
	v_pk_mul_f32 v[58:59], v[58:59], v[64:65] op_sel_hi:[1,0]
	v_pk_mul_f32 v[52:53], v[52:53], v[64:65] op_sel_hi:[1,0]
	v_pk_mul_f32 v[62:63], v[62:63], v[66:67]
	v_pk_mul_f32 v[54:55], v[54:55], v[64:65] op_sel_hi:[1,0]
	v_cvt_pk_bf16_f32 v61, v62, v63
	v_mul_f32_e32 v62, 0x3d372713, v56
	v_mul_f32_e32 v63, 0x3d372713, v57
	v_mul_f32_e32 v62, v56, v62
	v_mul_f32_e32 v63, v57, v63
	v_fma_f32 v62, v56, v62, v56
	v_fma_f32 v63, v57, v63, v57
	v_mul_f32_e32 v62, 0x3f4c422a, v62
	v_mul_f32_e32 v63, 0x3f4c422a, v63
	v_mul_f32_e32 v62, 0xc038aa3b, v62
	v_mul_f32_e32 v63, 0xc038aa3b, v63
	v_exp_f32_e32 v62, v62
	v_exp_f32_e32 v63, v63
	v_pk_mul_f32 v[48:49], v[48:49], v[64:65] op_sel_hi:[1,0]
	v_pk_mul_f32 v[50:51], v[50:51], v[64:65] op_sel_hi:[1,0]
	v_add_f32_e32 v62, 1.0, v62
	v_add_f32_e32 v63, 1.0, v63
	v_rcp_f32_e32 v62, v62
	v_rcp_f32_e32 v63, v63
	s_nop 0
	v_pk_mul_f32 v[56:57], v[56:57], v[62:63]
	v_mul_f32_e32 v62, 0x3d372713, v58
	v_mul_f32_e32 v63, 0x3d372713, v59
	v_mul_f32_e32 v62, v58, v62
	v_mul_f32_e32 v63, v59, v63
	v_fma_f32 v62, v58, v62, v58
; DI unsigned pk2(float a, float b) { f32x2 v = {a, b}; bf16x2_t r = __builtin_convertvector(v, bf16x2_t); return __builtin_bit_cast(unsigned, r); }
;     DI void operator()(gacc_t& acc, int pm, int pn, char* lds, int tid, int wr, int wc, int lane) const {
;     ...
;         for (int m = 0; m < 8; ++m) {
;             const float r = rl[m * 16];
; #pragma unroll
;             for (int n = 0; n < 4; ++n) {
;                 float g[4];
; #pragma unroll
;                 for (int j = 0; j < 4; ++j) {
;                     const float x = acc[m][n][j] * r;
;                     const float u = 0.7978845608028654f * (x + 0.044715f * x * x * x);
;                     const float e = __builtin_amdgcn_exp2f(-2.885390081777927f * u);
;                     g[j] = x * __builtin_amdgcn_rcpf(1.0f + e);
;                 }
;                 u32x2 w; w.x = pk2(g[0], g[1]); w.y = pk2(g[2], g[3]);
;                 *(u32x2*)(lbase + m * 16 * 528 + n * 32) = w;
;             }
;             __builtin_amdgcn_sched_barrier(0);
	v_fma_f32 v63, v59, v63, v59
	v_mul_f32_e32 v62, 0x3f4c422a, v62
	v_mul_f32_e32 v63, 0x3f4c422a, v63
	v_mul_f32_e32 v62, 0xc038aa3b, v62
	v_mul_f32_e32 v63, 0xc038aa3b, v63
	v_exp_f32_e32 v62, v62
	v_exp_f32_e32 v63, v63
	v_cvt_pk_bf16_f32 v56, v56, v57
	v_add_f32_e32 v62, 1.0, v62
	v_add_f32_e32 v63, 1.0, v63
	v_rcp_f32_e32 v62, v62
	v_rcp_f32_e32 v63, v63
	s_nop 0
	v_pk_mul_f32 v[58:59], v[58:59], v[62:63]
	s_nop 0
	v_cvt_pk_bf16_f32 v57, v58, v59
	v_add_u32_e32 v58, 0x8000, v126
	ds_write2_b64 v58, v[60:61], v[56:57] offset0:128 offset1:132
	v_mul_f32_e32 v56, 0x3d372713, v52
	v_mul_f32_e32 v57, 0x3d372713, v53
	v_mul_f32_e32 v56, v52, v56
	v_mul_f32_e32 v57, v53, v57
	v_fma_f32 v56, v52, v56, v52
	v_fma_f32 v57, v53, v57, v53
	v_mul_f32_e32 v56, 0x3f4c422a, v56
	v_mul_f32_e32 v57, 0x3f4c422a, v57
	v_mul_f32_e32 v56, 0xc038aa3b, v56
	v_mul_f32_e32 v57, 0xc038aa3b, v57
	v_exp_f32_e32 v56, v56
	v_exp_f32_e32 v57, v57
	v_add_f32_e32 v56, 1.0, v56
	v_add_f32_e32 v57, 1.0, v57
	v_rcp_f32_e32 v56, v56
	v_rcp_f32_e32 v57, v57
	s_nop 0
	v_pk_mul_f32 v[52:53], v[52:53], v[56:57]
	v_mul_f32_e32 v56, 0x3d372713, v54
	v_mul_f32_e32 v57, 0x3d372713, v55
	v_mul_f32_e32 v56, v54, v56
	v_mul_f32_e32 v57, v55, v57
	v_fma_f32 v56, v54, v56, v54
	v_fma_f32 v57, v55, v57, v55
	v_mul_f32_e32 v56, 0x3f4c422a, v56
	v_mul_f32_e32 v57, 0x3f4c422a, v57
	v_mul_f32_e32 v56, 0xc038aa3b, v56
	v_mul_f32_e32 v57, 0xc038aa3b, v57
	v_exp_f32_e32 v56, v56
	v_exp_f32_e32 v57, v57
	v_cvt_pk_bf16_f32 v52, v52, v53
	v_add_f32_e32 v56, 1.0, v56
	v_add_f32_e32 v57, 1.0, v57
	v_rcp_f32_e32 v56, v56
	v_rcp_f32_e32 v57, v57
	s_nop 0
	v_pk_mul_f32 v[54:55], v[54:55], v[56:57]
	s_nop 0
	v_cvt_pk_bf16_f32 v53, v54, v55
	v_mul_f32_e32 v54, 0x3d372713, v48
	v_mul_f32_e32 v55, 0x3d372713, v49
	v_mul_f32_e32 v54, v48, v54
	v_mul_f32_e32 v55, v49, v55
	v_fma_f32 v54, v48, v54, v48
	v_fma_f32 v55, v49, v55, v49
	v_mul_f32_e32 v54, 0x3f4c422a, v54
	v_mul_f32_e32 v55, 0x3f4c422a, v55
	v_mul_f32_e32 v54, 0xc038aa3b, v54
	v_mul_f32_e32 v55, 0xc038aa3b, v55
	v_exp_f32_e32 v54, v54
	v_exp_f32_e32 v55, v55
	v_add_f32_e32 v54, 1.0, v54
	v_add_f32_e32 v55, 1.0, v55
	v_rcp_f32_e32 v54, v54
	v_rcp_f32_e32 v55, v55
	s_nop 0
	v_pk_mul_f32 v[48:49], v[48:49], v[54:55]
	v_mul_f32_e32 v54, 0x3d372713, v50
	v_mul_f32_e32 v55, 0x3d372713, v51
	v_mul_f32_e32 v54, v50, v54
	v_mul_f32_e32 v55, v51, v55
	v_fma_f32 v54, v50, v54, v50
	v_fma_f32 v55, v51, v55, v51
	v_mul_f32_e32 v54, 0x3f4c422a, v54
	v_mul_f32_e32 v55, 0x3f4c422a, v55
	v_mul_f32_e32 v54, 0xc038aa3b, v54
	v_mul_f32_e32 v55, 0xc038aa3b, v55
	v_exp_f32_e32 v54, v54
	v_exp_f32_e32 v55, v55
	v_cvt_pk_bf16_f32 v48, v48, v49
	v_add_f32_e32 v54, 1.0, v54
	v_add_f32_e32 v55, 1.0, v55
	v_rcp_f32_e32 v54, v54
	v_rcp_f32_e32 v55, v55
	s_nop 0
	v_pk_mul_f32 v[50:51], v[50:51], v[54:55]
	s_nop 0
	v_cvt_pk_bf16_f32 v49, v50, v51
	ds_write2_b64 v58, v[52:53], v[48:49] offset0:136 offset1:140
	v_mov_b32_e32 v48, v249
	v_pk_mul_f32 v[44:45], v[44:45], v[48:49] op_sel_hi:[1,0]
	s_nop 0
	v_mul_f32_e32 v49, 0x3d372713, v44
	v_mul_f32_e32 v49, v44, v49
	v_fma_f32 v49, v44, v49, v44
	v_mul_f32_e32 v49, 0x3f4c422a, v49
	v_mul_f32_e32 v49, 0xc038aa3b, v49
	v_exp_f32_e32 v49, v49
	s_nop 0
	v_add_f32_e32 v49, 1.0, v49
	v_rcp_f32_e32 v50, v49
	v_mul_f32_e32 v49, 0x3d372713, v45
	v_mul_f32_e32 v49, v45, v49
	v_fma_f32 v49, v45, v49, v45
	v_mul_f32_e32 v49, 0x3f4c422a, v49
	v_mul_f32_e32 v49, 0xc038aa3b, v49
	v_exp_f32_e32 v49, v49
	s_nop 0
	v_add_f32_e32 v49, 1.0, v49
	v_pk_mul_f32 v[46:47], v[46:47], v[48:49] op_sel_hi:[1,0]
	v_rcp_f32_e32 v51, v49
	v_mul_f32_e32 v49, 0x3d372713, v46
	v_mul_f32_e32 v49, v46, v49
	v_fma_f32 v49, v46, v49, v46
	v_mul_f32_e32 v49, 0x3f4c422a, v49
	v_mul_f32_e32 v49, 0xc038aa3b, v49
	v_exp_f32_e32 v49, v49
	v_pk_mul_f32 v[44:45], v[44:45], v[50:51]
	v_add_f32_e32 v49, 1.0, v49
	v_rcp_f32_e32 v50, v49
	v_mul_f32_e32 v49, 0x3d372713, v47
	v_mul_f32_e32 v49, v47, v49
	v_fma_f32 v49, v47, v49, v47
	v_mul_f32_e32 v49, 0x3f4c422a, v49
	v_mul_f32_e32 v49, 0xc038aa3b, v49
	v_exp_f32_e32 v49, v49
	v_cvt_pk_bf16_f32 v44, v44, v45
	v_add_f32_e32 v49, 1.0, v49
	v_rcp_f32_e32 v51, v49
	v_pk_mul_f32 v[40:41], v[40:41], v[48:49] op_sel_hi:[1,0]
	v_pk_mul_f32 v[42:43], v[42:43], v[48:49] op_sel_hi:[1,0]
	v_pk_mul_f32 v[36:37], v[36:37], v[48:49] op_sel_hi:[1,0]
	v_pk_mul_f32 v[46:47], v[46:47], v[50:51]
	v_pk_mul_f32 v[38:39], v[38:39], v[48:49] op_sel_hi:[1,0]
	v_cvt_pk_bf16_f32 v45, v46, v47
	v_mul_f32_e32 v46, 0x3d372713, v40
	v_mul_f32_e32 v47, 0x3d372713, v41
	v_mul_f32_e32 v46, v40, v46
	v_mul_f32_e32 v47, v41, v47
	v_fma_f32 v46, v40, v46, v40
	v_fma_f32 v47, v41, v47, v41
	v_mul_f32_e32 v46, 0x3f4c422a, v46
	v_mul_f32_e32 v47, 0x3f4c422a, v47
	v_mul_f32_e32 v46, 0xc038aa3b, v46
	v_mul_f32_e32 v47, 0xc038aa3b, v47
	v_exp_f32_e32 v46, v46
	v_exp_f32_e32 v47, v47
	v_pk_mul_f32 v[32:33], v[32:33], v[48:49] op_sel_hi:[1,0]
	v_pk_mul_f32 v[34:35], v[34:35], v[48:49] op_sel_hi:[1,0]
	v_add_f32_e32 v46, 1.0, v46
	v_add_f32_e32 v47, 1.0, v47
	v_rcp_f32_e32 v46, v46
	v_rcp_f32_e32 v47, v47
	s_nop 0
	v_pk_mul_f32 v[40:41], v[40:41], v[46:47]
	v_mul_f32_e32 v46, 0x3d372713, v42
	v_mul_f32_e32 v47, 0x3d372713, v43
	v_mul_f32_e32 v46, v42, v46
	v_mul_f32_e32 v47, v43, v47
	v_fma_f32 v46, v42, v46, v42
	v_fma_f32 v47, v43, v47, v43
	v_mul_f32_e32 v46, 0x3f4c422a, v46
	v_mul_f32_e32 v47, 0x3f4c422a, v47
	v_mul_f32_e32 v46, 0xc038aa3b, v46
	v_mul_f32_e32 v47, 0xc038aa3b, v47
	v_exp_f32_e32 v46, v46
	v_exp_f32_e32 v47, v47
	v_cvt_pk_bf16_f32 v40, v40, v41
	v_add_f32_e32 v46, 1.0, v46
	v_add_f32_e32 v47, 1.0, v47
	v_rcp_f32_e32 v46, v46
	v_rcp_f32_e32 v47, v47
; DI unsigned pk2(float a, float b) { f32x2 v = {a, b}; bf16x2_t r = __builtin_convertvector(v, bf16x2_t); return __builtin_bit_cast(unsigned, r); }
;     DI void operator()(gacc_t& acc, int pm, int pn, char* lds, int tid, int wr, int wc, int lane) const {
;     ...
;         for (int m = 0; m < 8; ++m) {
;             const float r = rl[m * 16];
; #pragma unroll
;             for (int n = 0; n < 4; ++n) {
;                 float g[4];
; #pragma unroll
;                 for (int j = 0; j < 4; ++j) {
;                     const float x = acc[m][n][j] * r;
;                     const float u = 0.7978845608028654f * (x + 0.044715f * x * x * x);
;                     const float e = __builtin_amdgcn_exp2f(-2.885390081777927f * u);
;                     g[j] = x * __builtin_amdgcn_rcpf(1.0f + e);
;                 }
;                 u32x2 w; w.x = pk2(g[0], g[1]); w.y = pk2(g[2], g[3]);
;                 *(u32x2*)(lbase + m * 16 * 528 + n * 32) = w;
;             }
;             __builtin_amdgcn_sched_barrier(0);
	s_nop 0
	v_pk_mul_f32 v[42:43], v[42:43], v[46:47]
	s_nop 0
	v_cvt_pk_bf16_f32 v41, v42, v43
	v_add_u32_e32 v42, 0xa000, v126
	ds_write2_b64 v42, v[44:45], v[40:41] offset0:160 offset1:164
	v_mul_f32_e32 v40, 0x3d372713, v36
	v_mul_f32_e32 v41, 0x3d372713, v37
	v_mul_f32_e32 v40, v36, v40
	v_mul_f32_e32 v41, v37, v41
	v_fma_f32 v40, v36, v40, v36
	v_fma_f32 v41, v37, v41, v37
	v_mul_f32_e32 v40, 0x3f4c422a, v40
	v_mul_f32_e32 v41, 0x3f4c422a, v41
	v_mul_f32_e32 v40, 0xc038aa3b, v40
	v_mul_f32_e32 v41, 0xc038aa3b, v41
	v_exp_f32_e32 v40, v40
	v_exp_f32_e32 v41, v41
	v_add_f32_e32 v40, 1.0, v40
	v_add_f32_e32 v41, 1.0, v41
	v_rcp_f32_e32 v40, v40
	v_rcp_f32_e32 v41, v41
	s_nop 0
	v_pk_mul_f32 v[36:37], v[36:37], v[40:41]
	v_mul_f32_e32 v40, 0x3d372713, v38
	v_mul_f32_e32 v41, 0x3d372713, v39
	v_mul_f32_e32 v40, v38, v40
	v_mul_f32_e32 v41, v39, v41
	v_fma_f32 v40, v38, v40, v38
	v_fma_f32 v41, v39, v41, v39
	v_mul_f32_e32 v40, 0x3f4c422a, v40
	v_mul_f32_e32 v41, 0x3f4c422a, v41
	v_mul_f32_e32 v40, 0xc038aa3b, v40
	v_mul_f32_e32 v41, 0xc038aa3b, v41
	v_exp_f32_e32 v40, v40
	v_exp_f32_e32 v41, v41
	v_cvt_pk_bf16_f32 v36, v36, v37
	v_add_f32_e32 v40, 1.0, v40
	v_add_f32_e32 v41, 1.0, v41
	v_rcp_f32_e32 v40, v40
	v_rcp_f32_e32 v41, v41
	s_nop 0
	v_pk_mul_f32 v[38:39], v[38:39], v[40:41]
	s_nop 0
	v_cvt_pk_bf16_f32 v37, v38, v39
	v_mul_f32_e32 v38, 0x3d372713, v32
	v_mul_f32_e32 v39, 0x3d372713, v33
	v_mul_f32_e32 v38, v32, v38
	v_mul_f32_e32 v39, v33, v39
	v_fma_f32 v38, v32, v38, v32
	v_fma_f32 v39, v33, v39, v33
	v_mul_f32_e32 v38, 0x3f4c422a, v38
	v_mul_f32_e32 v39, 0x3f4c422a, v39
	v_mul_f32_e32 v38, 0xc038aa3b, v38
	v_mul_f32_e32 v39, 0xc038aa3b, v39
	v_exp_f32_e32 v38, v38
	v_exp_f32_e32 v39, v39
	v_add_f32_e32 v38, 1.0, v38
	v_add_f32_e32 v39, 1.0, v39
	v_rcp_f32_e32 v38, v38
	v_rcp_f32_e32 v39, v39
	s_nop 0
	v_pk_mul_f32 v[32:33], v[32:33], v[38:39]
	v_mul_f32_e32 v38, 0x3d372713, v34
	v_mul_f32_e32 v39, 0x3d372713, v35
	v_mul_f32_e32 v38, v34, v38
	v_mul_f32_e32 v39, v35, v39
	v_fma_f32 v38, v34, v38, v34
	v_fma_f32 v39, v35, v39, v35
	v_mul_f32_e32 v38, 0x3f4c422a, v38
	v_mul_f32_e32 v39, 0x3f4c422a, v39
	v_mul_f32_e32 v38, 0xc038aa3b, v38
	v_mul_f32_e32 v39, 0xc038aa3b, v39
	v_exp_f32_e32 v38, v38
	v_exp_f32_e32 v39, v39
	v_cvt_pk_bf16_f32 v32, v32, v33
	v_add_f32_e32 v38, 1.0, v38
	v_add_f32_e32 v39, 1.0, v39
	v_rcp_f32_e32 v38, v38
	v_rcp_f32_e32 v39, v39
	s_nop 0
	v_pk_mul_f32 v[34:35], v[34:35], v[38:39]
	s_nop 0
	v_cvt_pk_bf16_f32 v33, v34, v35
	ds_write2_b64 v42, v[36:37], v[32:33] offset0:168 offset1:172
	v_mov_b32_e32 v32, v250
	v_pk_mul_f32 v[28:29], v[28:29], v[32:33] op_sel_hi:[1,0]
	s_nop 0
	v_mul_f32_e32 v33, 0x3d372713, v28
	v_mul_f32_e32 v33, v28, v33
	v_fma_f32 v33, v28, v33, v28
	v_mul_f32_e32 v33, 0x3f4c422a, v33
	v_mul_f32_e32 v33, 0xc038aa3b, v33
	v_exp_f32_e32 v33, v33
	s_nop 0
	v_add_f32_e32 v33, 1.0, v33
	v_rcp_f32_e32 v34, v33
	v_mul_f32_e32 v33, 0x3d372713, v29
	v_mul_f32_e32 v33, v29, v33
	v_fma_f32 v33, v29, v33, v29
	v_mul_f32_e32 v33, 0x3f4c422a, v33
	v_mul_f32_e32 v33, 0xc038aa3b, v33
	v_exp_f32_e32 v33, v33
	s_nop 0
	v_add_f32_e32 v33, 1.0, v33
	v_pk_mul_f32 v[30:31], v[30:31], v[32:33] op_sel_hi:[1,0]
	v_rcp_f32_e32 v35, v33
	v_mul_f32_e32 v33, 0x3d372713, v30
	v_mul_f32_e32 v33, v30, v33
	v_fma_f32 v33, v30, v33, v30
	v_mul_f32_e32 v33, 0x3f4c422a, v33
	v_mul_f32_e32 v33, 0xc038aa3b, v33
	v_exp_f32_e32 v33, v33
	v_pk_mul_f32 v[28:29], v[28:29], v[34:35]
	v_add_f32_e32 v33, 1.0, v33
	v_rcp_f32_e32 v34, v33
	v_mul_f32_e32 v33, 0x3d372713, v31
	v_mul_f32_e32 v33, v31, v33
	v_fma_f32 v33, v31, v33, v31
	v_mul_f32_e32 v33, 0x3f4c422a, v33
	v_mul_f32_e32 v33, 0xc038aa3b, v33
	v_exp_f32_e32 v33, v33
	v_cvt_pk_bf16_f32 v28, v28, v29
	v_add_f32_e32 v33, 1.0, v33
	v_rcp_f32_e32 v35, v33
	v_pk_mul_f32 v[24:25], v[24:25], v[32:33] op_sel_hi:[1,0]
	v_pk_mul_f32 v[26:27], v[26:27], v[32:33] op_sel_hi:[1,0]
	v_pk_mul_f32 v[20:21], v[20:21], v[32:33] op_sel_hi:[1,0]
	v_pk_mul_f32 v[30:31], v[30:31], v[34:35]
	v_pk_mul_f32 v[22:23], v[22:23], v[32:33] op_sel_hi:[1,0]
	v_cvt_pk_bf16_f32 v29, v30, v31
	v_mul_f32_e32 v30, 0x3d372713, v24
	v_mul_f32_e32 v31, 0x3d372713, v25
	v_mul_f32_e32 v30, v24, v30
	v_mul_f32_e32 v31, v25, v31
	v_fma_f32 v30, v24, v30, v24
	v_fma_f32 v31, v25, v31, v25
	v_mul_f32_e32 v30, 0x3f4c422a, v30
	v_mul_f32_e32 v31, 0x3f4c422a, v31
	v_mul_f32_e32 v30, 0xc038aa3b, v30
	v_mul_f32_e32 v31, 0xc038aa3b, v31
	v_exp_f32_e32 v30, v30
	v_exp_f32_e32 v31, v31
	v_pk_mul_f32 v[16:17], v[16:17], v[32:33] op_sel_hi:[1,0]
	v_pk_mul_f32 v[18:19], v[18:19], v[32:33] op_sel_hi:[1,0]
	v_add_f32_e32 v30, 1.0, v30
	v_add_f32_e32 v31, 1.0, v31
	v_rcp_f32_e32 v30, v30
	v_rcp_f32_e32 v31, v31
	s_nop 0
	v_pk_mul_f32 v[24:25], v[24:25], v[30:31]
	v_mul_f32_e32 v30, 0x3d372713, v26
	v_mul_f32_e32 v31, 0x3d372713, v27
	v_mul_f32_e32 v30, v26, v30
	v_mul_f32_e32 v31, v27, v31
	v_fma_f32 v30, v26, v30, v26
	v_fma_f32 v31, v27, v31, v27
	v_mul_f32_e32 v30, 0x3f4c422a, v30
	v_mul_f32_e32 v31, 0x3f4c422a, v31
	v_mul_f32_e32 v30, 0xc038aa3b, v30
	v_mul_f32_e32 v31, 0xc038aa3b, v31
	v_exp_f32_e32 v30, v30
	v_exp_f32_e32 v31, v31
	v_cvt_pk_bf16_f32 v24, v24, v25
	v_add_f32_e32 v30, 1.0, v30
	v_add_f32_e32 v31, 1.0, v31
	v_rcp_f32_e32 v30, v30
	v_rcp_f32_e32 v31, v31
	s_nop 0
	v_pk_mul_f32 v[26:27], v[26:27], v[30:31]
	s_nop 0
	v_cvt_pk_bf16_f32 v25, v26, v27
	v_add_u32_e32 v26, 0xc000, v126
	ds_write2_b64 v26, v[28:29], v[24:25] offset0:192 offset1:196
	v_mul_f32_e32 v24, 0x3d372713, v20
	v_mul_f32_e32 v25, 0x3d372713, v21
	v_mul_f32_e32 v24, v20, v24
	v_mul_f32_e32 v25, v21, v25
	v_fma_f32 v24, v20, v24, v20
; DI unsigned pk2(float a, float b) { f32x2 v = {a, b}; bf16x2_t r = __builtin_convertvector(v, bf16x2_t); return __builtin_bit_cast(unsigned, r); }
;     DI void operator()(gacc_t& acc, int pm, int pn, char* lds, int tid, int wr, int wc, int lane) const {
;     ...
;         for (int m = 0; m < 8; ++m) {
;             const float r = rl[m * 16];
; #pragma unroll
;             for (int n = 0; n < 4; ++n) {
;                 float g[4];
; #pragma unroll
;                 for (int j = 0; j < 4; ++j) {
;                     const float x = acc[m][n][j] * r;
;                     const float u = 0.7978845608028654f * (x + 0.044715f * x * x * x);
;                     const float e = __builtin_amdgcn_exp2f(-2.885390081777927f * u);
;                     g[j] = x * __builtin_amdgcn_rcpf(1.0f + e);
;                 }
;                 u32x2 w; w.x = pk2(g[0], g[1]); w.y = pk2(g[2], g[3]);
;                 *(u32x2*)(lbase + m * 16 * 528 + n * 32) = w;
;             }
;             __builtin_amdgcn_sched_barrier(0);
	v_fma_f32 v25, v21, v25, v21
	v_mul_f32_e32 v24, 0x3f4c422a, v24
	v_mul_f32_e32 v25, 0x3f4c422a, v25
	v_mul_f32_e32 v24, 0xc038aa3b, v24
	v_mul_f32_e32 v25, 0xc038aa3b, v25
	v_exp_f32_e32 v24, v24
	v_exp_f32_e32 v25, v25
	v_add_f32_e32 v24, 1.0, v24
	v_add_f32_e32 v25, 1.0, v25
	v_rcp_f32_e32 v24, v24
	v_rcp_f32_e32 v25, v25
	s_nop 0
	v_pk_mul_f32 v[20:21], v[20:21], v[24:25]
	v_mul_f32_e32 v24, 0x3d372713, v22
	v_mul_f32_e32 v25, 0x3d372713, v23
	v_mul_f32_e32 v24, v22, v24
	v_mul_f32_e32 v25, v23, v25
	v_fma_f32 v24, v22, v24, v22
	v_fma_f32 v25, v23, v25, v23
	v_mul_f32_e32 v24, 0x3f4c422a, v24
	v_mul_f32_e32 v25, 0x3f4c422a, v25
	v_mul_f32_e32 v24, 0xc038aa3b, v24
	v_mul_f32_e32 v25, 0xc038aa3b, v25
	v_exp_f32_e32 v24, v24
	v_exp_f32_e32 v25, v25
	v_cvt_pk_bf16_f32 v20, v20, v21
	v_add_f32_e32 v24, 1.0, v24
	v_add_f32_e32 v25, 1.0, v25
	v_rcp_f32_e32 v24, v24
	v_rcp_f32_e32 v25, v25
	s_nop 0
	v_pk_mul_f32 v[22:23], v[22:23], v[24:25]
	s_nop 0
	v_cvt_pk_bf16_f32 v21, v22, v23
	v_mul_f32_e32 v22, 0x3d372713, v16
	v_mul_f32_e32 v23, 0x3d372713, v17
	v_mul_f32_e32 v22, v16, v22
	v_mul_f32_e32 v23, v17, v23
	v_fma_f32 v22, v16, v22, v16
	v_fma_f32 v23, v17, v23, v17
	v_mul_f32_e32 v22, 0x3f4c422a, v22
	v_mul_f32_e32 v23, 0x3f4c422a, v23
	v_mul_f32_e32 v22, 0xc038aa3b, v22
	v_mul_f32_e32 v23, 0xc038aa3b, v23
	v_exp_f32_e32 v22, v22
	v_exp_f32_e32 v23, v23
	v_add_f32_e32 v22, 1.0, v22
	v_add_f32_e32 v23, 1.0, v23
	v_rcp_f32_e32 v22, v22
	v_rcp_f32_e32 v23, v23
	s_nop 0
	v_pk_mul_f32 v[16:17], v[16:17], v[22:23]
	v_mul_f32_e32 v22, 0x3d372713, v18
	v_mul_f32_e32 v23, 0x3d372713, v19
	v_mul_f32_e32 v22, v18, v22
	v_mul_f32_e32 v23, v19, v23
	v_fma_f32 v22, v18, v22, v18
	v_fma_f32 v23, v19, v23, v19
	v_mul_f32_e32 v22, 0x3f4c422a, v22
	v_mul_f32_e32 v23, 0x3f4c422a, v23
	v_mul_f32_e32 v22, 0xc038aa3b, v22
	v_mul_f32_e32 v23, 0xc038aa3b, v23
	v_exp_f32_e32 v22, v22
	v_exp_f32_e32 v23, v23
	v_cvt_pk_bf16_f32 v16, v16, v17
	v_add_f32_e32 v22, 1.0, v22
	v_add_f32_e32 v23, 1.0, v23
	v_rcp_f32_e32 v22, v22
	v_rcp_f32_e32 v23, v23
	s_nop 0
	v_pk_mul_f32 v[18:19], v[18:19], v[22:23]
	s_nop 0
	v_cvt_pk_bf16_f32 v17, v18, v19
	ds_write2_b64 v26, v[20:21], v[16:17] offset0:200 offset1:204
	v_mov_b32_e32 v16, v251
	v_pk_mul_f32 v[12:13], v[12:13], v[16:17] op_sel_hi:[1,0]
	s_nop 0
	v_mul_f32_e32 v17, 0x3d372713, v12
	v_mul_f32_e32 v17, v12, v17
	v_fma_f32 v17, v12, v17, v12
	v_mul_f32_e32 v17, 0x3f4c422a, v17
	v_mul_f32_e32 v17, 0xc038aa3b, v17
	v_exp_f32_e32 v17, v17
	s_nop 0
	v_add_f32_e32 v17, 1.0, v17
	v_rcp_f32_e32 v18, v17
	v_mul_f32_e32 v17, 0x3d372713, v13
	v_mul_f32_e32 v17, v13, v17
	v_fma_f32 v17, v13, v17, v13
	v_mul_f32_e32 v17, 0x3f4c422a, v17
	v_mul_f32_e32 v17, 0xc038aa3b, v17
	v_exp_f32_e32 v17, v17
	s_nop 0
	v_add_f32_e32 v17, 1.0, v17
	v_pk_mul_f32 v[14:15], v[14:15], v[16:17] op_sel_hi:[1,0]
	v_rcp_f32_e32 v19, v17
	v_mul_f32_e32 v17, 0x3d372713, v14
	v_mul_f32_e32 v17, v14, v17
	v_fma_f32 v17, v14, v17, v14
	v_mul_f32_e32 v17, 0x3f4c422a, v17
	v_mul_f32_e32 v17, 0xc038aa3b, v17
	v_exp_f32_e32 v17, v17
	v_pk_mul_f32 v[12:13], v[12:13], v[18:19]
	v_add_f32_e32 v17, 1.0, v17
	v_rcp_f32_e32 v18, v17
	v_mul_f32_e32 v17, 0x3d372713, v15
	v_mul_f32_e32 v17, v15, v17
	v_fma_f32 v17, v15, v17, v15
	v_mul_f32_e32 v17, 0x3f4c422a, v17
	v_mul_f32_e32 v17, 0xc038aa3b, v17
	v_exp_f32_e32 v17, v17
	v_cvt_pk_bf16_f32 v12, v12, v13
	v_add_f32_e32 v17, 1.0, v17
	v_rcp_f32_e32 v19, v17
	v_pk_mul_f32 v[8:9], v[8:9], v[16:17] op_sel_hi:[1,0]
	v_pk_mul_f32 v[10:11], v[10:11], v[16:17] op_sel_hi:[1,0]
	v_pk_mul_f32 v[4:5], v[4:5], v[16:17] op_sel_hi:[1,0]
	v_pk_mul_f32 v[14:15], v[14:15], v[18:19]
	v_pk_mul_f32 v[6:7], v[6:7], v[16:17] op_sel_hi:[1,0]
	v_cvt_pk_bf16_f32 v13, v14, v15
	v_mul_f32_e32 v14, 0x3d372713, v8
	v_mul_f32_e32 v15, 0x3d372713, v9
	v_mul_f32_e32 v14, v8, v14
	v_mul_f32_e32 v15, v9, v15
	v_fma_f32 v14, v8, v14, v8
	v_fma_f32 v15, v9, v15, v9
	v_mul_f32_e32 v14, 0x3f4c422a, v14
	v_mul_f32_e32 v15, 0x3f4c422a, v15
	v_mul_f32_e32 v14, 0xc038aa3b, v14
	v_mul_f32_e32 v15, 0xc038aa3b, v15
	v_exp_f32_e32 v14, v14
	v_exp_f32_e32 v15, v15
	v_pk_mul_f32 v[0:1], v[0:1], v[16:17] op_sel_hi:[1,0]
	v_pk_mul_f32 v[2:3], v[2:3], v[16:17] op_sel_hi:[1,0]
	v_add_f32_e32 v14, 1.0, v14
	v_add_f32_e32 v15, 1.0, v15
	v_rcp_f32_e32 v14, v14
	v_rcp_f32_e32 v15, v15
	s_nop 0
	v_pk_mul_f32 v[8:9], v[8:9], v[14:15]
	v_mul_f32_e32 v14, 0x3d372713, v10
	v_mul_f32_e32 v15, 0x3d372713, v11
	v_mul_f32_e32 v14, v10, v14
	v_mul_f32_e32 v15, v11, v15
	v_fma_f32 v14, v10, v14, v10
	v_fma_f32 v15, v11, v15, v11
	v_mul_f32_e32 v14, 0x3f4c422a, v14
	v_mul_f32_e32 v15, 0x3f4c422a, v15
	v_mul_f32_e32 v14, 0xc038aa3b, v14
	v_mul_f32_e32 v15, 0xc038aa3b, v15
	v_exp_f32_e32 v14, v14
	v_exp_f32_e32 v15, v15
	v_cvt_pk_bf16_f32 v8, v8, v9
	v_add_f32_e32 v14, 1.0, v14
	v_add_f32_e32 v15, 1.0, v15
	v_rcp_f32_e32 v14, v14
	v_rcp_f32_e32 v15, v15
	s_nop 0
	v_pk_mul_f32 v[10:11], v[10:11], v[14:15]
	s_nop 0
	v_cvt_pk_bf16_f32 v9, v10, v11
	v_add_u32_e32 v10, 0xe000, v126
	ds_write2_b64 v10, v[12:13], v[8:9] offset0:224 offset1:228
	v_mul_f32_e32 v8, 0x3d372713, v4
	v_mul_f32_e32 v9, 0x3d372713, v5
	v_mul_f32_e32 v8, v4, v8
	v_mul_f32_e32 v9, v5, v9
	v_fma_f32 v8, v4, v8, v4
	v_fma_f32 v9, v5, v9, v5
	v_mul_f32_e32 v8, 0x3f4c422a, v8
	v_mul_f32_e32 v9, 0x3f4c422a, v9
	v_mul_f32_e32 v8, 0xc038aa3b, v8
	v_mul_f32_e32 v9, 0xc038aa3b, v9
	v_exp_f32_e32 v8, v8
	v_exp_f32_e32 v9, v9
	v_add_f32_e32 v8, 1.0, v8
	v_add_f32_e32 v9, 1.0, v9
	v_rcp_f32_e32 v8, v8
	v_rcp_f32_e32 v9, v9
	s_nop 0
	v_pk_mul_f32 v[4:5], v[4:5], v[8:9]
	v_mul_f32_e32 v8, 0x3d372713, v6
	v_mul_f32_e32 v9, 0x3d372713, v7
; DI unsigned pk2(float a, float b) { f32x2 v = {a, b}; bf16x2_t r = __builtin_convertvector(v, bf16x2_t); return __builtin_bit_cast(unsigned, r); }
; DI void store_tile_from_lds(const char* lds, bf16_t* dst, long ld, int tid) {
; #pragma unroll
;     for (int k = 0; k < 16; ++k) {
;         const int id = tid + NTH * k, row = id >> 5, ch = id & 31;
;         const u32x4 v = *(const u32x4*)(lds + row * 528 + ch * 16);
;         *(u32x4*)(dst + (long)row * ld + ch * 8) = v;
;     }
; }
;     DI void operator()(gacc_t& acc, int pm, int pn, char* lds, int tid, int wr, int wc, int lane) const {
;     ...
;         for (int m = 0; m < 8; ++m) {
;             const float r = rl[m * 16];
; #pragma unroll
;             for (int n = 0; n < 4; ++n) {
;                 float g[4];
; #pragma unroll
;                 for (int j = 0; j < 4; ++j) {
;                     const float x = acc[m][n][j] * r;
;                     const float u = 0.7978845608028654f * (x + 0.044715f * x * x * x);
;                     const float e = __builtin_amdgcn_exp2f(-2.885390081777927f * u);
;                     g[j] = x * __builtin_amdgcn_rcpf(1.0f + e);
;                 }
;                 u32x2 w; w.x = pk2(g[0], g[1]); w.y = pk2(g[2], g[3]);
;                 *(u32x2*)(lbase + m * 16 * 528 + n * 32) = w;
;             }
;             __builtin_amdgcn_sched_barrier(0);
;         }
;         __syncthreads();
;         store_tile_from_lds(lds, z + (long)pm * 256 * 2048 + pn * 256, 2048, tid);
;         __syncthreads();
	v_mul_f32_e32 v8, v6, v8
	v_mul_f32_e32 v9, v7, v9
	v_fma_f32 v8, v6, v8, v6
	v_fma_f32 v9, v7, v9, v7
	v_mul_f32_e32 v8, 0x3f4c422a, v8
	v_mul_f32_e32 v9, 0x3f4c422a, v9
	v_mul_f32_e32 v8, 0xc038aa3b, v8
	v_mul_f32_e32 v9, 0xc038aa3b, v9
	v_exp_f32_e32 v8, v8
	v_exp_f32_e32 v9, v9
	v_cvt_pk_bf16_f32 v4, v4, v5
	v_add_f32_e32 v8, 1.0, v8
	v_add_f32_e32 v9, 1.0, v9
	v_rcp_f32_e32 v8, v8
	v_rcp_f32_e32 v9, v9
	s_nop 0
	v_pk_mul_f32 v[6:7], v[6:7], v[8:9]
	s_nop 0
	v_cvt_pk_bf16_f32 v5, v6, v7
	v_mul_f32_e32 v6, 0x3d372713, v0
	v_mul_f32_e32 v7, 0x3d372713, v1
	v_mul_f32_e32 v6, v0, v6
	v_mul_f32_e32 v7, v1, v7
	v_fma_f32 v6, v0, v6, v0
	v_fma_f32 v7, v1, v7, v1
	v_mul_f32_e32 v6, 0x3f4c422a, v6
	v_mul_f32_e32 v7, 0x3f4c422a, v7
	v_mul_f32_e32 v6, 0xc038aa3b, v6
	v_mul_f32_e32 v7, 0xc038aa3b, v7
	v_exp_f32_e32 v6, v6
	v_exp_f32_e32 v7, v7
	v_add_f32_e32 v6, 1.0, v6
	v_add_f32_e32 v7, 1.0, v7
	v_rcp_f32_e32 v6, v6
	v_rcp_f32_e32 v7, v7
	s_nop 0
	v_pk_mul_f32 v[0:1], v[0:1], v[6:7]
	v_mul_f32_e32 v6, 0x3d372713, v2
	v_mul_f32_e32 v7, 0x3d372713, v3
	v_mul_f32_e32 v6, v2, v6
	v_mul_f32_e32 v7, v3, v7
	v_fma_f32 v6, v2, v6, v2
	v_fma_f32 v7, v3, v7, v3
	v_mul_f32_e32 v6, 0x3f4c422a, v6
	v_mul_f32_e32 v7, 0x3f4c422a, v7
	v_mul_f32_e32 v6, 0xc038aa3b, v6
	v_mul_f32_e32 v7, 0xc038aa3b, v7
	v_exp_f32_e32 v6, v6
	v_exp_f32_e32 v7, v7
	v_cvt_pk_bf16_f32 v0, v0, v1
	v_add_f32_e32 v6, 1.0, v6
	v_add_f32_e32 v7, 1.0, v7
	v_rcp_f32_e32 v6, v6
	v_rcp_f32_e32 v7, v7
	s_nop 0
	v_pk_mul_f32 v[2:3], v[2:3], v[6:7]
	s_nop 0
	v_cvt_pk_bf16_f32 v1, v2, v3
	ds_write2_b64 v10, v[4:5], v[0:1] offset0:232 offset1:236
	s_lshl_b64 s[8:9], s[8:9], 20
	s_add_u32 s8, s70, s8
	s_addc_u32 s9, s71, s9
	s_lshl_b32 s6, s6, 8
	s_ashr_i32 s7, s6, 31
	v_lshlrev_b32_e32 v0, 4, v125
	s_lshl_b64 s[6:7], s[6:7], 1
	v_and_b32_e32 v146, 0x1f0, v0
	s_add_u32 s6, s8, s6
	v_add_u32_e32 v4, 0, v146
	v_ashrrev_i32_e32 v6, 5, v125
	s_addc_u32 s7, s9, s7
	v_mad_u64_u32 v[0:1], s[8:9], v6, s3, v[4:5]
	s_waitcnt lgkmcnt(0)
	s_barrier
	ds_read_b128 v[0:3], v0
	v_ashrrev_i32_e32 v7, 31, v6
	v_lshl_add_u64 v[8:9], s[6:7], 0, v[146:147]
	v_lshlrev_b64 v[6:7], 12, v[6:7]
	v_lshl_add_u64 v[6:7], v[8:9], 0, v[6:7]
	s_waitcnt lgkmcnt(0)
	flat_store_dwordx4 v[6:7], v[0:3]
	s_add_i32 s17, s17, 1
	s_nop 0
	v_add_u32_e32 v0, 0x200, v125
	v_ashrrev_i32_e32 v6, 5, v0
	v_mad_u64_u32 v[0:1], s[6:7], v6, s3, v[4:5]
	ds_read_b128 v[0:3], v0
	v_ashrrev_i32_e32 v7, 31, v6
	v_lshlrev_b64 v[6:7], 12, v[6:7]
	v_lshl_add_u64 v[6:7], v[8:9], 0, v[6:7]
	s_waitcnt lgkmcnt(0)
	flat_store_dwordx4 v[6:7], v[0:3]
	s_nop 1
	v_add_u32_e32 v0, 0x400, v125
	v_ashrrev_i32_e32 v6, 5, v0
	v_mad_u64_u32 v[0:1], s[6:7], v6, s3, v[4:5]
	ds_read_b128 v[0:3], v0
	v_ashrrev_i32_e32 v7, 31, v6
	v_lshlrev_b64 v[6:7], 12, v[6:7]
	v_lshl_add_u64 v[6:7], v[8:9], 0, v[6:7]
	s_waitcnt lgkmcnt(0)
	flat_store_dwordx4 v[6:7], v[0:3]
	s_nop 1
	v_add_u32_e32 v0, 0x600, v125
	v_ashrrev_i32_e32 v6, 5, v0
	v_mad_u64_u32 v[0:1], s[6:7], v6, s3, v[4:5]
	ds_read_b128 v[0:3], v0
	v_ashrrev_i32_e32 v7, 31, v6
	v_lshlrev_b64 v[6:7], 12, v[6:7]
	v_lshl_add_u64 v[6:7], v[8:9], 0, v[6:7]
	s_waitcnt lgkmcnt(0)
	flat_store_dwordx4 v[6:7], v[0:3]
	s_nop 1
	v_add_u32_e32 v0, 0x800, v125
	v_ashrrev_i32_e32 v6, 5, v0
	v_mad_u64_u32 v[0:1], s[6:7], v6, s3, v[4:5]
	ds_read_b128 v[0:3], v0
	v_ashrrev_i32_e32 v7, 31, v6
	v_lshlrev_b64 v[6:7], 12, v[6:7]
	v_lshl_add_u64 v[6:7], v[8:9], 0, v[6:7]
	s_waitcnt lgkmcnt(0)
	flat_store_dwordx4 v[6:7], v[0:3]
	s_nop 1
	v_add_u32_e32 v0, 0xa00, v125
	v_ashrrev_i32_e32 v6, 5, v0
	v_mad_u64_u32 v[0:1], s[6:7], v6, s3, v[4:5]
	ds_read_b128 v[0:3], v0
	v_ashrrev_i32_e32 v7, 31, v6
	v_lshlrev_b64 v[6:7], 12, v[6:7]
	v_lshl_add_u64 v[6:7], v[8:9], 0, v[6:7]
	s_waitcnt lgkmcnt(0)
	flat_store_dwordx4 v[6:7], v[0:3]
	s_nop 1
	v_add_u32_e32 v0, 0xc00, v125
	v_ashrrev_i32_e32 v6, 5, v0
	v_mad_u64_u32 v[0:1], s[6:7], v6, s3, v[4:5]
	ds_read_b128 v[0:3], v0
	v_ashrrev_i32_e32 v7, 31, v6
	v_lshlrev_b64 v[6:7], 12, v[6:7]
	v_lshl_add_u64 v[6:7], v[8:9], 0, v[6:7]
	s_waitcnt lgkmcnt(0)
	flat_store_dwordx4 v[6:7], v[0:3]
	s_nop 1
	v_add_u32_e32 v0, 0xe00, v125
	v_ashrrev_i32_e32 v6, 5, v0
	v_mad_u64_u32 v[0:1], s[6:7], v6, s3, v[4:5]
	ds_read_b128 v[0:3], v0
	v_ashrrev_i32_e32 v7, 31, v6
	v_lshlrev_b64 v[6:7], 12, v[6:7]
	v_lshl_add_u64 v[6:7], v[8:9], 0, v[6:7]
	s_waitcnt lgkmcnt(0)
	flat_store_dwordx4 v[6:7], v[0:3]
	s_nop 1
	v_add_u32_e32 v0, 0x1000, v125
	v_ashrrev_i32_e32 v6, 5, v0
	v_mad_u64_u32 v[0:1], s[6:7], v6, s3, v[4:5]
	ds_read_b128 v[0:3], v0
	v_ashrrev_i32_e32 v7, 31, v6
	v_lshlrev_b64 v[6:7], 12, v[6:7]
	v_lshl_add_u64 v[6:7], v[8:9], 0, v[6:7]
	s_waitcnt lgkmcnt(0)
	flat_store_dwordx4 v[6:7], v[0:3]
	s_nop 1
	v_add_u32_e32 v0, 0x1200, v125
	v_ashrrev_i32_e32 v6, 5, v0
	v_mad_u64_u32 v[0:1], s[6:7], v6, s3, v[4:5]
	ds_read_b128 v[0:3], v0
	v_ashrrev_i32_e32 v7, 31, v6
	v_lshlrev_b64 v[6:7], 12, v[6:7]
	v_lshl_add_u64 v[6:7], v[8:9], 0, v[6:7]
	s_waitcnt lgkmcnt(0)
	flat_store_dwordx4 v[6:7], v[0:3]
	s_nop 1
	v_add_u32_e32 v0, 0x1400, v125
	v_ashrrev_i32_e32 v6, 5, v0
	v_mad_u64_u32 v[0:1], s[6:7], v6, s3, v[4:5]
	ds_read_b128 v[0:3], v0
	v_ashrrev_i32_e32 v7, 31, v6
	v_lshlrev_b64 v[6:7], 12, v[6:7]
	v_lshl_add_u64 v[6:7], v[8:9], 0, v[6:7]
	s_waitcnt lgkmcnt(0)
	flat_store_dwordx4 v[6:7], v[0:3]
	s_nop 1
	v_add_u32_e32 v0, 0x1600, v125
	v_ashrrev_i32_e32 v6, 5, v0
	v_mad_u64_u32 v[0:1], s[6:7], v6, s3, v[4:5]
	ds_read_b128 v[0:3], v0
	v_ashrrev_i32_e32 v7, 31, v6
	v_lshlrev_b64 v[6:7], 12, v[6:7]
	v_lshl_add_u64 v[6:7], v[8:9], 0, v[6:7]
	s_waitcnt lgkmcnt(0)
	flat_store_dwordx4 v[6:7], v[0:3]
	s_nop 1
	v_add_u32_e32 v0, 0x1800, v125
	v_ashrrev_i32_e32 v6, 5, v0
	v_mad_u64_u32 v[0:1], s[6:7], v6, s3, v[4:5]
	ds_read_b128 v[0:3], v0
	v_ashrrev_i32_e32 v7, 31, v6
	v_lshlrev_b64 v[6:7], 12, v[6:7]
	v_lshl_add_u64 v[6:7], v[8:9], 0, v[6:7]
	s_waitcnt lgkmcnt(0)
	flat_store_dwordx4 v[6:7], v[0:3]
	s_nop 1
	v_add_u32_e32 v0, 0x1a00, v125
	v_ashrrev_i32_e32 v6, 5, v0
	v_mad_u64_u32 v[0:1], s[6:7], v6, s3, v[4:5]
	ds_read_b128 v[0:3], v0
	v_ashrrev_i32_e32 v7, 31, v6
	v_lshlrev_b64 v[6:7], 12, v[6:7]
	v_lshl_add_u64 v[6:7], v[8:9], 0, v[6:7]
	s_waitcnt lgkmcnt(0)
	flat_store_dwordx4 v[6:7], v[0:3]
	s_nop 1
	v_add_u32_e32 v0, 0x1c00, v125
	v_ashrrev_i32_e32 v6, 5, v0
	v_mad_u64_u32 v[0:1], s[6:7], v6, s3, v[4:5]
	ds_read_b128 v[0:3], v0
	v_ashrrev_i32_e32 v7, 31, v6
	v_lshlrev_b64 v[6:7], 12, v[6:7]
	v_lshl_add_u64 v[6:7], v[8:9], 0, v[6:7]
	s_waitcnt lgkmcnt(0)
	flat_store_dwordx4 v[6:7], v[0:3]
	s_nop 1
	v_add_u32_e32 v0, 0x1e00, v125
	v_ashrrev_i32_e32 v6, 5, v0
	v_mad_u64_u32 v[0:1], s[6:7], v6, s3, v[4:5]
	ds_read_b128 v[0:3], v0
	v_ashrrev_i32_e32 v7, 31, v6
	s_mul_i32 s6, s17, s28
	v_lshlrev_b64 v[4:5], 12, v[6:7]
	s_add_i32 s6, s6, s2
	v_lshl_add_u64 v[4:5], v[8:9], 0, v[4:5]
	s_cmpk_lt_i32 s6, 0xa00
	s_waitcnt lgkmcnt(0)
	flat_store_dwordx4 v[4:5], v[0:3]
	s_waitcnt lgkmcnt(0)
	s_barrier
	s_cbranch_scc1 .LBB0_370

; #define MFMA16(a, b, c) __builtin_amdgcn_mfma_f32_16x16x32_bf16((a), (b), (c), 0, 0, 0)
; DI bf16x8 ldfrag(const char* lds, int row, int chunk) { return *(const bf16x8*)(lds + swz(row, chunk)); }
; #define GEMM_SG1() do { __builtin_amdgcn_sched_group_barrier(0x100, 1, 0); __builtin_amdgcn_sched_group_barrier(0x008, 4, 0); } while (0)
; #define GEMM_SG2() do { __builtin_amdgcn_sched_group_barrier(0x100, 2, 0); __builtin_amdgcn_sched_group_barrier(0x008, 4, 0); } while (0)
; template <bool RSTD, bool SWAP>
; DI void gemm_tile(gacc_t& acc, const bf16_t* __restrict__ A, int lda, const bf16_t* __restrict__ Bt, int ldb, int K,
;                   char* lds, int tid, int wr, int wc, int lane, const float* ssq_row) {
;     ...
;     for (int kt = 0; kt < nk; ++kt) {
;         const char* cur = lds + (kt & 1) * 65536;
;         if (kt + 1 < nk) GEMM_ISSUE(kt + 1, (kt + 1) & 1);
;         bf16x8 bfr[2][4], afr[3];
; #pragma unroll
;         for (int n = 0; n < 4; ++n) bfr[0][n] = ldfrag(cur + 32768, wc * 64 + n * 16 + fr, fq);
;         afr[0] = ldfrag(cur, wr * 128 + fr, fq);
;         afr[1] = ldfrag(cur, wr * 128 + 16 + fr, fq);
; #pragma unroll
;         for (int idx = 0; idx < 16; ++idx) {
;             const int ks = idx >> 3, m = idx & 7;
;             if (idx < 14) afr[(idx + 2) % 3] = ldfrag(cur, wr * 128 + ((idx + 2) & 7) * 16 + fr, ((idx + 2) >> 3) * 4 + fq);
;             if (ks == 0 && m >= 2 && m < 6) bfr[1][m - 2] = ldfrag(cur + 32768, wc * 64 + (m - 2) * 16 + fr, 4 + fq);
; #pragma unroll
;             for (int n = 0; n < 4; ++n) acc[m][n] = SWAP ? MFMA16(bfr[ks][n], afr[idx % 3], acc[m][n]) : MFMA16(afr[idx % 3], bfr[ks][n], acc[m][n]);
;         }
;         __builtin_amdgcn_sched_group_barrier(0x100, 6, 0);
;     ...
;         GEMM_SG1(); GEMM_SG1(); GEMM_SG2(); GEMM_SG2(); GEMM_SG2(); GEMM_SG2(); GEMM_SG1(); GEMM_SG1();
;         GEMM_SG1(); GEMM_SG1(); GEMM_SG1(); GEMM_SG1(); GEMM_SG1(); GEMM_SG1();
;         __builtin_amdgcn_sched_group_barrier(0x008, 8, 0);
;         __builtin_amdgcn_sched_barrier(0);
;         asm volatile("s_waitcnt vmcnt(0)" ::: "memory");
;         __syncthreads();
;     }
.LBB0_618:
	s_add_i32 s45, s44, 0xffff0000
	s_and_b32 s45, s45, 0x10000
	s_add_i32 s45, s45, 0
	v_add_u32_e32 v146, s45, v144
	v_add3_u32 v161, v146, v150, v151
	v_add_u32_e32 v166, v146, v148
	ds_read_b128 v[162:165], v161 offset:32768
	ds_read_b128 v[172:175], v161 offset:34816
	ds_read_b128 v[180:183], v161 offset:36864
	ds_read_b128 v[186:189], v161 offset:38912
	ds_read_b128 v[176:179], v166
	ds_read_b128 v[190:193], v166 offset:2048
	v_add_u32_e32 v161, v146, v152
	ds_read_b128 v[194:197], v166 offset:4096
	v_lshl_add_u64 v[240:241], v[140:141], 0, s[12:13]
	v_lshl_add_u64 v[242:243], v[138:139], 0, s[12:13]
	s_and_b32 s48, s44, 0x10000
	s_add_i32 s48, s43, s48
	s_mov_b64 s[46:47], 0x2ee40080
	v_lshl_add_u64 v[232:233], v[240:241], 0, s[46:47]
	s_mov_b32 m0, s48
	v_mfma_f32_16x16x32_bf16 v[60:63], v[198:201], v[214:217], v[60:63]
	global_load_lds_dwordx4 v[232:233], off
	v_mfma_f32_16x16x32_bf16 v[56:59], v[202:205], v[214:217], v[56:59]
	s_mov_b64 s[46:47], 0x1c80080
	v_lshl_add_u64 v[234:235], v[242:243], 0, s[46:47]
	s_add_i32 m0, s48, 0x8000
	v_mfma_f32_16x16x32_bf16 v[52:55], v[206:209], v[214:217], v[52:55]
	global_load_lds_dwordx4 v[234:235], off
	v_mfma_f32_16x16x32_bf16 v[48:51], v[210:213], v[214:217], v[48:51]
	s_mov_b64 s[46:47], 0x2ee60080
	v_lshl_add_u64 v[232:233], v[240:241], 0, s[46:47]
	s_add_i32 m0, s48, 0x2000
	v_mfma_f32_16x16x32_bf16 v[44:47], v[198:201], v[218:221], v[44:47]
	global_load_lds_dwordx4 v[232:233], off
	v_mfma_f32_16x16x32_bf16 v[40:43], v[202:205], v[218:221], v[40:43]
	s_mov_b64 s[46:47], 0x1ca0080
	v_lshl_add_u64 v[234:235], v[242:243], 0, s[46:47]
	s_add_i32 m0, s48, 0xa000
	v_mfma_f32_16x16x32_bf16 v[36:39], v[206:209], v[218:221], v[36:39]
	global_load_lds_dwordx4 v[234:235], off
	v_mfma_f32_16x16x32_bf16 v[32:35], v[210:213], v[218:221], v[32:35]
	s_mov_b64 s[46:47], 0x2ee80080
	v_lshl_add_u64 v[232:233], v[240:241], 0, s[46:47]
	s_add_i32 m0, s48, 0x4000
	v_mfma_f32_16x16x32_bf16 v[28:31], v[198:201], v[222:225], v[28:31]
	global_load_lds_dwordx4 v[232:233], off
	v_mfma_f32_16x16x32_bf16 v[24:27], v[202:205], v[222:225], v[24:27]
	s_mov_b64 s[46:47], 0x1cc0080
	v_lshl_add_u64 v[234:235], v[242:243], 0, s[46:47]
	s_add_i32 m0, s48, 0xc000
	v_mfma_f32_16x16x32_bf16 v[20:23], v[206:209], v[222:225], v[20:23]
	global_load_lds_dwordx4 v[234:235], off
	v_mfma_f32_16x16x32_bf16 v[16:19], v[210:213], v[222:225], v[16:19]
	s_mov_b64 s[46:47], 0x2eea0080
	v_lshl_add_u64 v[232:233], v[240:241], 0, s[46:47]
	s_add_i32 m0, s48, 0x6000
	v_mfma_f32_16x16x32_bf16 v[12:15], v[198:201], v[236:239], v[12:15]
	global_load_lds_dwordx4 v[232:233], off
	v_mfma_f32_16x16x32_bf16 v[8:11], v[202:205], v[236:239], v[8:11]
	s_mov_b64 s[46:47], 0x1ce0080
	v_lshl_add_u64 v[234:235], v[242:243], 0, s[46:47]
	s_add_i32 m0, s48, 0xe000
	v_mfma_f32_16x16x32_bf16 v[4:7], v[206:209], v[236:239], v[4:7]
	global_load_lds_dwordx4 v[234:235], off
	v_mfma_f32_16x16x32_bf16 v[0:3], v[210:213], v[236:239], v[0:3]
	s_waitcnt lgkmcnt(2)
	v_mfma_f32_16x16x32_bf16 v[124:127], v[162:165], v[176:179], v[124:127]
	v_add_u32_e32 v146, v146, v154
	v_mfma_f32_16x16x32_bf16 v[120:123], v[172:175], v[176:179], v[120:123]
	v_mfma_f32_16x16x32_bf16 v[116:119], v[180:183], v[176:179], v[116:119]
	v_mfma_f32_16x16x32_bf16 v[112:115], v[186:189], v[176:179], v[112:115]
	ds_read_b128 v[176:179], v161
	v_add_u32_e32 v161, s45, v149
	v_add_u32_e32 v167, v161, v153
	s_waitcnt lgkmcnt(2)
	v_mfma_f32_16x16x32_bf16 v[108:111], v[162:165], v[190:193], v[108:111]
	v_mfma_f32_16x16x32_bf16 v[104:107], v[172:175], v[190:193], v[104:107]
	v_mfma_f32_16x16x32_bf16 v[100:103], v[180:183], v[190:193], v[100:103]
	v_mfma_f32_16x16x32_bf16 v[96:99], v[186:189], v[190:193], v[96:99]
	ds_read_b128 v[190:193], v166 offset:8192
	ds_read_b128 v[198:201], v167 offset:32768
	s_waitcnt lgkmcnt(3)
	v_mfma_f32_16x16x32_bf16 v[92:95], v[162:165], v[194:197], v[92:95]
	v_mfma_f32_16x16x32_bf16 v[88:91], v[172:175], v[194:197], v[88:91]
	v_mfma_f32_16x16x32_bf16 v[84:87], v[180:183], v[194:197], v[84:87]
	v_mfma_f32_16x16x32_bf16 v[80:83], v[186:189], v[194:197], v[80:83]
	ds_read_b128 v[194:197], v166 offset:10240
	ds_read_b128 v[202:205], v167 offset:34816
	s_waitcnt lgkmcnt(4)
	v_mfma_f32_16x16x32_bf16 v[76:79], v[162:165], v[176:179], v[76:79]
	v_mfma_f32_16x16x32_bf16 v[72:75], v[172:175], v[176:179], v[72:75]
	v_mfma_f32_16x16x32_bf16 v[68:71], v[180:183], v[176:179], v[68:71]
	v_mfma_f32_16x16x32_bf16 v[64:67], v[186:189], v[176:179], v[64:67]
	ds_read_b128 v[176:179], v166 offset:12288
	v_add_u32_e32 v166, v161, v155
	ds_read_b128 v[206:209], v167 offset:36864
	s_waitcnt lgkmcnt(5)
	v_mfma_f32_16x16x32_bf16 v[60:63], v[162:165], v[190:193], v[60:63]
	v_mfma_f32_16x16x32_bf16 v[56:59], v[172:175], v[190:193], v[56:59]
	v_mfma_f32_16x16x32_bf16 v[52:55], v[180:183], v[190:193], v[52:55]
	v_mfma_f32_16x16x32_bf16 v[48:51], v[186:189], v[190:193], v[48:51]
	ds_read_b128 v[210:213], v166 offset:38912
	ds_read_b128 v[190:193], v146
	v_add_u32_e32 v146, v161, v148
	s_waitcnt lgkmcnt(5)
	v_mfma_f32_16x16x32_bf16 v[44:47], v[162:165], v[194:197], v[44:47]
	v_add_u32_e32 v166, v161, v152
	v_mfma_f32_16x16x32_bf16 v[40:43], v[172:175], v[194:197], v[40:43]
	v_mfma_f32_16x16x32_bf16 v[36:39], v[180:183], v[194:197], v[36:39]
	v_mfma_f32_16x16x32_bf16 v[32:35], v[186:189], v[194:197], v[32:35]
	ds_read_b128 v[194:197], v146
	v_add_u32_e32 v230, v161, v154
	s_waitcnt lgkmcnt(4)
	v_mfma_f32_16x16x32_bf16 v[28:31], v[162:165], v[176:179], v[28:31]
	v_mfma_f32_16x16x32_bf16 v[24:27], v[172:175], v[176:179], v[24:27]
	v_mfma_f32_16x16x32_bf16 v[20:23], v[180:183], v[176:179], v[20:23]
	v_mfma_f32_16x16x32_bf16 v[16:19], v[186:189], v[176:179], v[16:19]
	ds_read_b128 v[176:179], v146 offset:2048
	s_waitcnt lgkmcnt(2)
; #define MFMA16(a, b, c) __builtin_amdgcn_mfma_f32_16x16x32_bf16((a), (b), (c), 0, 0, 0)
; DI bf16x8 ldfrag(const char* lds, int row, int chunk) { return *(const bf16x8*)(lds + swz(row, chunk)); }
; #define GEMM_SG1() do { __builtin_amdgcn_sched_group_barrier(0x100, 1, 0); __builtin_amdgcn_sched_group_barrier(0x008, 4, 0); } while (0)
; #define GEMM_SG2() do { __builtin_amdgcn_sched_group_barrier(0x100, 2, 0); __builtin_amdgcn_sched_group_barrier(0x008, 4, 0); } while (0)
; template <bool RSTD, bool SWAP>
; DI void gemm_tile(gacc_t& acc, const bf16_t* __restrict__ A, int lda, const bf16_t* __restrict__ Bt, int ldb, int K,
;                   char* lds, int tid, int wr, int wc, int lane, const float* ssq_row) {
;     ...
;         for (int idx = 0; idx < 16; ++idx) {
;             const int ks = idx >> 3, m = idx & 7;
;             if (idx < 14) afr[(idx + 2) % 3] = ldfrag(cur, wr * 128 + ((idx + 2) & 7) * 16 + fr, ((idx + 2) >> 3) * 4 + fq);
;             if (ks == 0 && m >= 2 && m < 6) bfr[1][m - 2] = ldfrag(cur + 32768, wc * 64 + (m - 2) * 16 + fr, 4 + fq);
; #pragma unroll
;             for (int n = 0; n < 4; ++n) acc[m][n] = SWAP ? MFMA16(bfr[ks][n], afr[idx % 3], acc[m][n]) : MFMA16(afr[idx % 3], bfr[ks][n], acc[m][n]);
;         }
;         __builtin_amdgcn_sched_group_barrier(0x100, 6, 0);
;     ...
;         GEMM_SG1(); GEMM_SG1(); GEMM_SG2(); GEMM_SG2(); GEMM_SG2(); GEMM_SG2(); GEMM_SG1(); GEMM_SG1();
;         GEMM_SG1(); GEMM_SG1(); GEMM_SG1(); GEMM_SG1(); GEMM_SG1(); GEMM_SG1();
;         __builtin_amdgcn_sched_group_barrier(0x008, 8, 0);
;         __builtin_amdgcn_sched_barrier(0);
;         asm volatile("s_waitcnt vmcnt(0)" ::: "memory");
;         __syncthreads();
;     }
	v_mfma_f32_16x16x32_bf16 v[12:15], v[162:165], v[190:193], v[12:15]
	v_mfma_f32_16x16x32_bf16 v[8:11], v[172:175], v[190:193], v[8:11]
	v_mfma_f32_16x16x32_bf16 v[4:7], v[180:183], v[190:193], v[4:7]
	v_mfma_f32_16x16x32_bf16 v[0:3], v[186:189], v[190:193], v[0:3]
	ds_read_b128 v[162:165], v146 offset:4096
	s_waitcnt lgkmcnt(2)
	v_mfma_f32_16x16x32_bf16 v[124:127], v[198:201], v[194:197], v[124:127]
	v_mfma_f32_16x16x32_bf16 v[120:123], v[202:205], v[194:197], v[120:123]
	v_mfma_f32_16x16x32_bf16 v[116:119], v[206:209], v[194:197], v[116:119]
	v_mfma_f32_16x16x32_bf16 v[112:115], v[210:213], v[194:197], v[112:115]
	ds_read_b128 v[172:175], v166
	ds_read_b128 v[214:217], v146 offset:8192
	s_waitcnt lgkmcnt(3)
	v_mfma_f32_16x16x32_bf16 v[108:111], v[198:201], v[176:179], v[108:111]
	v_mfma_f32_16x16x32_bf16 v[104:107], v[202:205], v[176:179], v[104:107]
	v_mfma_f32_16x16x32_bf16 v[100:103], v[206:209], v[176:179], v[100:103]
	v_mfma_f32_16x16x32_bf16 v[96:99], v[210:213], v[176:179], v[96:99]
	ds_read_b128 v[218:221], v146 offset:10240
	s_waitcnt lgkmcnt(3)
	v_mfma_f32_16x16x32_bf16 v[92:95], v[198:201], v[162:165], v[92:95]
	v_mfma_f32_16x16x32_bf16 v[88:91], v[202:205], v[162:165], v[88:91]
	v_mfma_f32_16x16x32_bf16 v[84:87], v[206:209], v[162:165], v[84:87]
	v_mfma_f32_16x16x32_bf16 v[80:83], v[210:213], v[162:165], v[80:83]
	ds_read_b128 v[222:225], v146 offset:12288
	ds_read_b128 v[236:239], v230
	s_waitcnt lgkmcnt(4)
	v_mfma_f32_16x16x32_bf16 v[76:79], v[198:201], v[172:175], v[76:79]
	v_mfma_f32_16x16x32_bf16 v[72:75], v[202:205], v[172:175], v[72:75]
	v_mfma_f32_16x16x32_bf16 v[68:71], v[206:209], v[172:175], v[68:71]
	v_mfma_f32_16x16x32_bf16 v[64:67], v[210:213], v[172:175], v[64:67]
	s_waitcnt lgkmcnt(0)
	s_waitcnt vmcnt(0)
	s_add_u32 s12, s12, 0x80
	s_addc_u32 s13, s13, 0
	s_add_i32 s44, s44, 0x10000
	s_cmpk_lg_i32 s12, 0x780
	s_waitcnt vmcnt(0)
	s_barrier
	s_cbranch_scc1 .LBB0_618
	v_mfma_f32_16x16x32_bf16 v[60:63], v[198:201], v[214:217], v[60:63]
	v_mfma_f32_16x16x32_bf16 v[56:59], v[202:205], v[214:217], v[56:59]
	v_mfma_f32_16x16x32_bf16 v[52:55], v[206:209], v[214:217], v[52:55]
	v_mfma_f32_16x16x32_bf16 v[48:51], v[210:213], v[214:217], v[48:51]
	v_mfma_f32_16x16x32_bf16 v[44:47], v[198:201], v[218:221], v[44:47]
	v_mfma_f32_16x16x32_bf16 v[40:43], v[202:205], v[218:221], v[40:43]
	v_mfma_f32_16x16x32_bf16 v[36:39], v[206:209], v[218:221], v[36:39]
	v_mfma_f32_16x16x32_bf16 v[32:35], v[210:213], v[218:221], v[32:35]
	v_mfma_f32_16x16x32_bf16 v[28:31], v[198:201], v[222:225], v[28:31]
	v_mfma_f32_16x16x32_bf16 v[24:27], v[202:205], v[222:225], v[24:27]
	v_mfma_f32_16x16x32_bf16 v[20:23], v[206:209], v[222:225], v[20:23]
	v_mfma_f32_16x16x32_bf16 v[16:19], v[210:213], v[222:225], v[16:19]
	v_mfma_f32_16x16x32_bf16 v[12:15], v[198:201], v[236:239], v[12:15]
	v_mfma_f32_16x16x32_bf16 v[8:11], v[202:205], v[236:239], v[8:11]
	v_mfma_f32_16x16x32_bf16 v[4:7], v[206:209], v[236:239], v[4:7]
	v_mfma_f32_16x16x32_bf16 v[0:3], v[210:213], v[236:239], v[0:3]
	ds_read_b128 v[138:141], v160
	ds_read_b128 v[162:165], v160 offset:2048
	ds_read_b128 v[176:179], v160 offset:4096
	ds_read_b128 v[180:183], v160 offset:6144
	v_add_u32_e32 v146, v156, v148
	ds_read_b128 v[172:175], v146
	ds_read_b128 v[186:189], v146 offset:2048
	v_add_u32_e32 v161, v156, v152
	ds_read_b128 v[190:193], v146 offset:4096
	s_waitcnt lgkmcnt(2)
	v_mfma_f32_16x16x32_bf16 v[124:127], v[138:141], v[172:175], v[124:127]
	v_mfma_f32_16x16x32_bf16 v[120:123], v[162:165], v[172:175], v[120:123]
	v_mfma_f32_16x16x32_bf16 v[116:119], v[176:179], v[172:175], v[116:119]
	v_mfma_f32_16x16x32_bf16 v[112:115], v[180:183], v[172:175], v[112:115]
	ds_read_b128 v[172:175], v161
	v_add_u32_e32 v161, v157, v153
	s_waitcnt lgkmcnt(2)
	v_mfma_f32_16x16x32_bf16 v[108:111], v[138:141], v[186:189], v[108:111]
	v_mfma_f32_16x16x32_bf16 v[104:107], v[162:165], v[186:189], v[104:107]
	v_mfma_f32_16x16x32_bf16 v[100:103], v[176:179], v[186:189], v[100:103]
	v_mfma_f32_16x16x32_bf16 v[96:99], v[180:183], v[186:189], v[96:99]
	ds_read_b128 v[186:189], v146 offset:8192
	ds_read_b128 v[194:197], v161
	s_waitcnt lgkmcnt(3)
	v_mfma_f32_16x16x32_bf16 v[92:95], v[138:141], v[190:193], v[92:95]
	v_mfma_f32_16x16x32_bf16 v[88:91], v[162:165], v[190:193], v[88:91]
	v_mfma_f32_16x16x32_bf16 v[84:87], v[176:179], v[190:193], v[84:87]
	v_mfma_f32_16x16x32_bf16 v[80:83], v[180:183], v[190:193], v[80:83]
	ds_read_b128 v[190:193], v146 offset:10240
	ds_read_b128 v[198:201], v161 offset:2048
	s_waitcnt lgkmcnt(4)
	v_mfma_f32_16x16x32_bf16 v[76:79], v[138:141], v[172:175], v[76:79]
	v_mfma_f32_16x16x32_bf16 v[72:75], v[162:165], v[172:175], v[72:75]
	v_mfma_f32_16x16x32_bf16 v[68:71], v[176:179], v[172:175], v[68:71]
	v_mfma_f32_16x16x32_bf16 v[64:67], v[180:183], v[172:175], v[64:67]
	ds_read_b128 v[172:175], v146 offset:12288
	v_add_u32_e32 v146, v156, v154
	ds_read_b128 v[202:205], v161 offset:4096
	s_waitcnt lgkmcnt(5)
	v_mfma_f32_16x16x32_bf16 v[60:63], v[138:141], v[186:189], v[60:63]
	v_mfma_f32_16x16x32_bf16 v[56:59], v[162:165], v[186:189], v[56:59]
	v_mfma_f32_16x16x32_bf16 v[52:55], v[176:179], v[186:189], v[52:55]
	v_mfma_f32_16x16x32_bf16 v[48:51], v[180:183], v[186:189], v[48:51]
	ds_read_b128 v[186:189], v146
	v_add_u32_e32 v146, v157, v155
	ds_read_b128 v[206:209], v146 offset:6144
	v_add_u32_e32 v146, v158, v148
	s_waitcnt lgkmcnt(5)
; #define MFMA16(a, b, c) __builtin_amdgcn_mfma_f32_16x16x32_bf16((a), (b), (c), 0, 0, 0)
; template <bool RSTD, bool SWAP>
; DI void gemm_tile(gacc_t& acc, const bf16_t* __restrict__ A, int lda, const bf16_t* __restrict__ Bt, int ldb, int K,
;                   char* lds, int tid, int wr, int wc, int lane, const float* ssq_row) {
;     ...
;         for (int idx = 0; idx < 16; ++idx) {
;             const int ks = idx >> 3, m = idx & 7;
;             if (idx < 14) afr[(idx + 2) % 3] = ldfrag(cur, wr * 128 + ((idx + 2) & 7) * 16 + fr, ((idx + 2) >> 3) * 4 + fq);
;             if (ks == 0 && m >= 2 && m < 6) bfr[1][m - 2] = ldfrag(cur + 32768, wc * 64 + (m - 2) * 16 + fr, 4 + fq);
; #pragma unroll
;             for (int n = 0; n < 4; ++n) acc[m][n] = SWAP ? MFMA16(bfr[ks][n], afr[idx % 3], acc[m][n]) : MFMA16(afr[idx % 3], bfr[ks][n], acc[m][n]);
;         }
;         __builtin_amdgcn_sched_group_barrier(0x100, 6, 0);
;     ...
;         GEMM_SG1(); GEMM_SG1(); GEMM_SG2(); GEMM_SG2(); GEMM_SG2(); GEMM_SG2(); GEMM_SG1(); GEMM_SG1();
;         GEMM_SG1(); GEMM_SG1(); GEMM_SG1(); GEMM_SG1(); GEMM_SG1(); GEMM_SG1();
;         __builtin_amdgcn_sched_group_barrier(0x008, 8, 0);
;         __builtin_amdgcn_sched_barrier(0);
;         asm volatile("s_waitcnt vmcnt(0)" ::: "memory");
;         __syncthreads();
;     DI void operator()(gacc_t& acc, int pm, int pn, char* lds, int tid, int wr, int wc, int lane) const {
;         asm volatile("" : "+v"(tid), "+v"(lane));
;         const int fr = lane & 15, fq = lane >> 4;
;         constexpr int RS = 528;
;         const float* rl = (const float*)(lds + RSTD_OFF) + wr * 128 + fr;
;         {
;             char* lbase = lds + (wr * 128 + fr) * RS + (wc * 64 + 4 * fq) * 2;
;             bf16_t* hrow = halo + (long)(pm * 4) * 5632 + pn * 256 + wc * 64 + 4 * fq;
; #pragma unroll
;             for (int m = 0; m < 8; ++m) {
;                 const float r = rl[m * 16];
; #pragma unroll
;                 for (int n = 0; n < 4; ++n) {
;                     u32x2 w; w.x = pk2(acc[m][n][0] * r, acc[m][n][1] * r); w.y = pk2(acc[m][n][2] * r, acc[m][n][3] * r);
;                     *(u32x2*)(lbase + m * 16 * RS + n * 32) = w;
;                     if (m == 0 && wr == 0 && fr < 2) *(u32x2*)(hrow + fr * 5632 + n * 16) = w;
;                     if (m == 7 && wr == 1 && fr >= 14) *(u32x2*)(hrow + (fr - 12) * 5632 + n * 16) = w;
	v_mfma_f32_16x16x32_bf16 v[44:47], v[138:141], v[190:193], v[44:47]
	v_mfma_f32_16x16x32_bf16 v[40:43], v[162:165], v[190:193], v[40:43]
	v_mfma_f32_16x16x32_bf16 v[36:39], v[176:179], v[190:193], v[36:39]
	v_mfma_f32_16x16x32_bf16 v[32:35], v[180:183], v[190:193], v[32:35]
	ds_read_b128 v[190:193], v146
	s_waitcnt lgkmcnt(4)
	v_mfma_f32_16x16x32_bf16 v[28:31], v[138:141], v[172:175], v[28:31]
	v_mfma_f32_16x16x32_bf16 v[24:27], v[162:165], v[172:175], v[24:27]
	v_mfma_f32_16x16x32_bf16 v[20:23], v[176:179], v[172:175], v[20:23]
	v_mfma_f32_16x16x32_bf16 v[16:19], v[180:183], v[172:175], v[16:19]
	ds_read_b128 v[172:175], v146 offset:2048
	s_waitcnt lgkmcnt(3)
	v_mfma_f32_16x16x32_bf16 v[12:15], v[138:141], v[186:189], v[12:15]
	v_mfma_f32_16x16x32_bf16 v[8:11], v[162:165], v[186:189], v[8:11]
	v_mfma_f32_16x16x32_bf16 v[4:7], v[176:179], v[186:189], v[4:7]
	v_mfma_f32_16x16x32_bf16 v[138:141], v[180:183], v[186:189], v[0:3]
	s_nop 2
	ds_read_b128 v[0:3], v146 offset:4096
	s_waitcnt lgkmcnt(2)
	v_mfma_f32_16x16x32_bf16 v[164:167], v[194:197], v[190:193], v[124:127]
	v_mfma_f32_16x16x32_bf16 v[120:123], v[198:201], v[190:193], v[120:123]
	s_nop 1
	v_add_u32_e32 v124, v158, v152
	v_mfma_f32_16x16x32_bf16 v[116:119], v[202:205], v[190:193], v[116:119]
	v_mfma_f32_16x16x32_bf16 v[112:115], v[206:209], v[190:193], v[112:115]
	ds_read_b128 v[124:127], v124
	s_waitcnt lgkmcnt(2)
	v_mfma_f32_16x16x32_bf16 v[108:111], v[194:197], v[172:175], v[108:111]
	v_mfma_f32_16x16x32_bf16 v[104:107], v[198:201], v[172:175], v[104:107]
	v_mfma_f32_16x16x32_bf16 v[100:103], v[202:205], v[172:175], v[100:103]
	v_mfma_f32_16x16x32_bf16 v[96:99], v[206:209], v[172:175], v[96:99]
	ds_read_b128 v[172:175], v146 offset:8192
	s_waitcnt lgkmcnt(2)
	v_mfma_f32_16x16x32_bf16 v[92:95], v[194:197], v[0:3], v[92:95]
	v_mfma_f32_16x16x32_bf16 v[88:91], v[198:201], v[0:3], v[88:91]
	v_mfma_f32_16x16x32_bf16 v[84:87], v[202:205], v[0:3], v[84:87]
	v_mfma_f32_16x16x32_bf16 v[80:83], v[206:209], v[0:3], v[80:83]
	ds_read_b128 v[0:3], v146 offset:10240
	s_waitcnt lgkmcnt(2)
	v_mfma_f32_16x16x32_bf16 v[76:79], v[194:197], v[124:127], v[76:79]
	v_mfma_f32_16x16x32_bf16 v[72:75], v[198:201], v[124:127], v[72:75]
	v_mfma_f32_16x16x32_bf16 v[68:71], v[202:205], v[124:127], v[68:71]
	v_mfma_f32_16x16x32_bf16 v[64:67], v[206:209], v[124:127], v[64:67]
	ds_read_b128 v[124:127], v146 offset:12288
	v_add_u32_e32 v146, v158, v154
	s_waitcnt lgkmcnt(2)
	v_mfma_f32_16x16x32_bf16 v[60:63], v[194:197], v[172:175], v[60:63]
	v_mfma_f32_16x16x32_bf16 v[56:59], v[198:201], v[172:175], v[56:59]
	v_mfma_f32_16x16x32_bf16 v[52:55], v[202:205], v[172:175], v[52:55]
	v_mfma_f32_16x16x32_bf16 v[48:51], v[206:209], v[172:175], v[48:51]
	ds_read_b128 v[172:175], v146
	s_waitcnt lgkmcnt(2)
	v_mfma_f32_16x16x32_bf16 v[44:47], v[194:197], v[0:3], v[44:47]
	v_mfma_f32_16x16x32_bf16 v[40:43], v[198:201], v[0:3], v[40:43]
	v_mfma_f32_16x16x32_bf16 v[36:39], v[202:205], v[0:3], v[36:39]
	v_mfma_f32_16x16x32_bf16 v[32:35], v[206:209], v[0:3], v[32:35]
	s_waitcnt lgkmcnt(1)
	v_mfma_f32_16x16x32_bf16 v[28:31], v[194:197], v[124:127], v[28:31]
	v_mfma_f32_16x16x32_bf16 v[24:27], v[198:201], v[124:127], v[24:27]
	v_mfma_f32_16x16x32_bf16 v[20:23], v[202:205], v[124:127], v[20:23]
	v_mfma_f32_16x16x32_bf16 v[16:19], v[206:209], v[124:127], v[16:19]
	s_waitcnt lgkmcnt(0)
	v_mfma_f32_16x16x32_bf16 v[12:15], v[194:197], v[172:175], v[12:15]
	v_mfma_f32_16x16x32_bf16 v[8:11], v[198:201], v[172:175], v[8:11]
	v_mfma_f32_16x16x32_bf16 v[0:3], v[202:205], v[172:175], v[4:7]
	v_mfma_f32_16x16x32_bf16 v[4:7], v[206:209], v[172:175], v[138:141]
	s_lshl_b32 s12, s42, 2
	s_mul_i32 s13, s42, 0xb000
	s_mul_hi_i32 s12, s12, 0x2c00
	s_add_u32 s43, s22, s13
	v_mov_b32_e32 v124, v142
	v_mov_b32_e32 v140, v133
	s_addc_u32 s44, s23, s12
	s_lshl_b32 s12, s40, 8
	s_waitcnt vmcnt(0)
	s_barrier
	s_ashr_i32 s13, s12, 31
	v_and_b32_e32 v162, 15, v124
	v_or_b32_e32 v125, v162, v145
	v_ashrrev_i32_e32 v124, 2, v124
	s_lshl_b64 s[12:13], s[12:13], 1
	v_mul_lo_u32 v125, v125, s3
	v_and_b32_e32 v124, -4, v124
	s_add_u32 s12, s43, s12
	v_add_u32_e32 v125, 0, v125
	v_add_lshl_u32 v126, v124, v132, 1
	s_addc_u32 s13, s44, s13
	v_lshlrev_b32_e32 v146, 1, v132
	v_lshl_add_u32 v161, v162, 2, v159
	v_add_u32_e32 v141, v125, v126
	v_lshl_add_u64 v[126:127], s[12:13], 0, v[146:147]
	v_ashrrev_i32_e32 v125, 31, v124
	v_lshl_add_u64 v[124:125], v[124:125], 1, v[126:127]
	ds_read_b32 v244, v161
	ds_read_b32 v245, v161 offset:64
	ds_read_b32 v246, v161 offset:128
	ds_read_b32 v247, v161 offset:192
	ds_read_b32 v248, v161 offset:256
	ds_read_b32 v249, v161 offset:320
	ds_read_b32 v250, v161 offset:384
	ds_read_b32 v251, v161 offset:448
	v_mul_u32_u24_e32 v127, 0x1600, v162
	v_cmp_gt_u32_e32 vcc, 2, v162
	v_lshlrev_b32_e32 v146, 1, v127
	v_lshl_add_u64 v[124:125], v[124:125], 0, v[146:147]
	s_waitcnt lgkmcnt(0)
	v_mov_b32_e32 v126, v244
	v_pk_mul_f32 v[138:139], v[164:165], v[126:127] op_sel_hi:[1,0]
	v_pk_mul_f32 v[164:165], v[166:167], v[126:127] op_sel_hi:[1,0]
	s_and_b64 s[12:13], s[8:9], vcc
	v_cvt_pk_bf16_f32 v138, v138, v139
	v_cvt_pk_bf16_f32 v139, v164, v165
	ds_write_b64 v141, v[138:139]
	s_and_saveexec_b64 s[44:45], s[12:13]
	s_cbranch_execz .LBB0_621
	flat_store_dwordx2 v[124:125], v[138:139]

; DI unsigned pk2(float a, float b) { f32x2 v = {a, b}; bf16x2_t r = __builtin_convertvector(v, bf16x2_t); return __builtin_bit_cast(unsigned, r); }
;     DI void operator()(gacc_t& acc, int pm, int pn, char* lds, int tid, int wr, int wc, int lane) const {
;     ...
;         const float* rl = (const float*)(lds + RSTD_OFF) + wr * 128 + fr;
;         {
;             char* lbase = lds + (wr * 128 + fr) * RS + (wc * 64 + 4 * fq) * 2;
;             bf16_t* hrow = halo + (long)(pm * 4) * 5632 + pn * 256 + wc * 64 + 4 * fq;
; #pragma unroll
;             for (int m = 0; m < 8; ++m) {
;                 const float r = rl[m * 16];
; #pragma unroll
;                 for (int n = 0; n < 4; ++n) {
;                     u32x2 w; w.x = pk2(acc[m][n][0] * r, acc[m][n][1] * r); w.y = pk2(acc[m][n][2] * r, acc[m][n][3] * r);
;                     *(u32x2*)(lbase + m * 16 * RS + n * 32) = w;
;                     if (m == 0 && wr == 0 && fr < 2) *(u32x2*)(hrow + fr * 5632 + n * 16) = w;
;                     if (m == 7 && wr == 1 && fr >= 14) *(u32x2*)(hrow + (fr - 12) * 5632 + n * 16) = w;
.LBB0_627:
	s_or_b64 exec, exec, s[44:45]
	v_mov_b32_e32 v112, v245
	v_cmp_lt_u32_e32 vcc, 13, v162
	s_and_b64 s[12:13], s[6:7], vcc
	v_pk_mul_f32 v[108:109], v[108:109], v[112:113] op_sel_hi:[1,0]
	v_pk_mul_f32 v[110:111], v[110:111], v[112:113] op_sel_hi:[1,0]
	v_pk_mul_f32 v[104:105], v[104:105], v[112:113] op_sel_hi:[1,0]
	v_pk_mul_f32 v[106:107], v[106:107], v[112:113] op_sel_hi:[1,0]
	v_pk_mul_f32 v[100:101], v[100:101], v[112:113] op_sel_hi:[1,0]
	v_pk_mul_f32 v[102:103], v[102:103], v[112:113] op_sel_hi:[1,0]
	v_pk_mul_f32 v[96:97], v[96:97], v[112:113] op_sel_hi:[1,0]
	v_pk_mul_f32 v[98:99], v[98:99], v[112:113] op_sel_hi:[1,0]
	v_cvt_pk_bf16_f32 v108, v108, v109
	v_cvt_pk_bf16_f32 v109, v110, v111
	v_cvt_pk_bf16_f32 v104, v104, v105
	v_cvt_pk_bf16_f32 v105, v106, v107
	v_add_u32_e32 v106, 0x2000, v141
	v_cvt_pk_bf16_f32 v100, v100, v101
	v_cvt_pk_bf16_f32 v101, v102, v103
	v_cvt_pk_bf16_f32 v96, v96, v97
	v_cvt_pk_bf16_f32 v97, v98, v99
	ds_write2_b64 v106, v[108:109], v[104:105] offset0:32 offset1:36
	ds_write2_b64 v106, v[100:101], v[96:97] offset0:40 offset1:44
	v_mov_b32_e32 v96, v246
	v_pk_mul_f32 v[92:93], v[92:93], v[96:97] op_sel_hi:[1,0]
	v_pk_mul_f32 v[94:95], v[94:95], v[96:97] op_sel_hi:[1,0]
	v_pk_mul_f32 v[88:89], v[88:89], v[96:97] op_sel_hi:[1,0]
	v_pk_mul_f32 v[90:91], v[90:91], v[96:97] op_sel_hi:[1,0]
	v_pk_mul_f32 v[84:85], v[84:85], v[96:97] op_sel_hi:[1,0]
	v_pk_mul_f32 v[86:87], v[86:87], v[96:97] op_sel_hi:[1,0]
	v_pk_mul_f32 v[80:81], v[80:81], v[96:97] op_sel_hi:[1,0]
	v_pk_mul_f32 v[82:83], v[82:83], v[96:97] op_sel_hi:[1,0]
	v_cvt_pk_bf16_f32 v92, v92, v93
	v_cvt_pk_bf16_f32 v93, v94, v95
	v_cvt_pk_bf16_f32 v88, v88, v89
	v_cvt_pk_bf16_f32 v89, v90, v91
	v_add_u32_e32 v90, 0x4000, v141
	v_cvt_pk_bf16_f32 v84, v84, v85
	v_cvt_pk_bf16_f32 v85, v86, v87
	v_cvt_pk_bf16_f32 v80, v80, v81
	v_cvt_pk_bf16_f32 v81, v82, v83
	ds_write2_b64 v90, v[92:93], v[88:89] offset0:64 offset1:68
	ds_write2_b64 v90, v[84:85], v[80:81] offset0:72 offset1:76
	v_mov_b32_e32 v80, v247
	v_pk_mul_f32 v[76:77], v[76:77], v[80:81] op_sel_hi:[1,0]
	v_pk_mul_f32 v[78:79], v[78:79], v[80:81] op_sel_hi:[1,0]
	v_pk_mul_f32 v[72:73], v[72:73], v[80:81] op_sel_hi:[1,0]
	v_pk_mul_f32 v[74:75], v[74:75], v[80:81] op_sel_hi:[1,0]
	v_pk_mul_f32 v[68:69], v[68:69], v[80:81] op_sel_hi:[1,0]
	v_pk_mul_f32 v[70:71], v[70:71], v[80:81] op_sel_hi:[1,0]
	v_pk_mul_f32 v[64:65], v[64:65], v[80:81] op_sel_hi:[1,0]
	v_pk_mul_f32 v[66:67], v[66:67], v[80:81] op_sel_hi:[1,0]
	v_cvt_pk_bf16_f32 v76, v76, v77
	v_cvt_pk_bf16_f32 v77, v78, v79
	v_cvt_pk_bf16_f32 v72, v72, v73
	v_cvt_pk_bf16_f32 v73, v74, v75
	v_add_u32_e32 v74, 0x6000, v141
	v_cvt_pk_bf16_f32 v68, v68, v69
	v_cvt_pk_bf16_f32 v69, v70, v71
	v_cvt_pk_bf16_f32 v64, v64, v65
	v_cvt_pk_bf16_f32 v65, v66, v67
	ds_write2_b64 v74, v[76:77], v[72:73] offset0:96 offset1:100
	ds_write2_b64 v74, v[68:69], v[64:65] offset0:104 offset1:108
	v_mov_b32_e32 v64, v248
	v_pk_mul_f32 v[60:61], v[60:61], v[64:65] op_sel_hi:[1,0]
	v_pk_mul_f32 v[62:63], v[62:63], v[64:65] op_sel_hi:[1,0]
	v_pk_mul_f32 v[56:57], v[56:57], v[64:65] op_sel_hi:[1,0]
	v_pk_mul_f32 v[58:59], v[58:59], v[64:65] op_sel_hi:[1,0]
	v_pk_mul_f32 v[52:53], v[52:53], v[64:65] op_sel_hi:[1,0]
	v_pk_mul_f32 v[54:55], v[54:55], v[64:65] op_sel_hi:[1,0]
	v_pk_mul_f32 v[48:49], v[48:49], v[64:65] op_sel_hi:[1,0]
	v_pk_mul_f32 v[50:51], v[50:51], v[64:65] op_sel_hi:[1,0]
	v_cvt_pk_bf16_f32 v60, v60, v61
	v_cvt_pk_bf16_f32 v61, v62, v63
	v_cvt_pk_bf16_f32 v56, v56, v57
	v_cvt_pk_bf16_f32 v57, v58, v59
	v_add_u32_e32 v58, 0x8000, v141
	v_cvt_pk_bf16_f32 v52, v52, v53
	v_cvt_pk_bf16_f32 v53, v54, v55
	v_cvt_pk_bf16_f32 v48, v48, v49
	v_cvt_pk_bf16_f32 v49, v50, v51
	ds_write2_b64 v58, v[60:61], v[56:57] offset0:128 offset1:132
	ds_write2_b64 v58, v[52:53], v[48:49] offset0:136 offset1:140
	v_mov_b32_e32 v48, v249
	v_pk_mul_f32 v[44:45], v[44:45], v[48:49] op_sel_hi:[1,0]
	v_pk_mul_f32 v[46:47], v[46:47], v[48:49] op_sel_hi:[1,0]
	v_pk_mul_f32 v[40:41], v[40:41], v[48:49] op_sel_hi:[1,0]
	v_pk_mul_f32 v[42:43], v[42:43], v[48:49] op_sel_hi:[1,0]
	v_pk_mul_f32 v[36:37], v[36:37], v[48:49] op_sel_hi:[1,0]
	v_pk_mul_f32 v[38:39], v[38:39], v[48:49] op_sel_hi:[1,0]
	v_pk_mul_f32 v[32:33], v[32:33], v[48:49] op_sel_hi:[1,0]
	v_pk_mul_f32 v[34:35], v[34:35], v[48:49] op_sel_hi:[1,0]
	v_cvt_pk_bf16_f32 v44, v44, v45
	v_cvt_pk_bf16_f32 v45, v46, v47
	v_cvt_pk_bf16_f32 v40, v40, v41
	v_cvt_pk_bf16_f32 v41, v42, v43
	v_add_u32_e32 v42, 0xa000, v141
	v_cvt_pk_bf16_f32 v36, v36, v37
	v_cvt_pk_bf16_f32 v37, v38, v39
	v_cvt_pk_bf16_f32 v32, v32, v33
	v_cvt_pk_bf16_f32 v33, v34, v35
	ds_write2_b64 v42, v[44:45], v[40:41] offset0:160 offset1:164
	ds_write2_b64 v42, v[36:37], v[32:33] offset0:168 offset1:172
	v_mov_b32_e32 v32, v250
	v_pk_mul_f32 v[28:29], v[28:29], v[32:33] op_sel_hi:[1,0]
	v_pk_mul_f32 v[30:31], v[30:31], v[32:33] op_sel_hi:[1,0]
	v_pk_mul_f32 v[24:25], v[24:25], v[32:33] op_sel_hi:[1,0]
	v_pk_mul_f32 v[26:27], v[26:27], v[32:33] op_sel_hi:[1,0]
	v_pk_mul_f32 v[20:21], v[20:21], v[32:33] op_sel_hi:[1,0]
	v_pk_mul_f32 v[22:23], v[22:23], v[32:33] op_sel_hi:[1,0]
	v_pk_mul_f32 v[16:17], v[16:17], v[32:33] op_sel_hi:[1,0]
	v_pk_mul_f32 v[18:19], v[18:19], v[32:33] op_sel_hi:[1,0]
	v_cvt_pk_bf16_f32 v28, v28, v29
	v_cvt_pk_bf16_f32 v29, v30, v31
	v_cvt_pk_bf16_f32 v24, v24, v25
	v_cvt_pk_bf16_f32 v25, v26, v27
	v_add_u32_e32 v26, 0xc000, v141
	v_cvt_pk_bf16_f32 v20, v20, v21
	v_cvt_pk_bf16_f32 v21, v22, v23
	v_cvt_pk_bf16_f32 v16, v16, v17
	v_cvt_pk_bf16_f32 v17, v18, v19
	ds_write2_b64 v26, v[28:29], v[24:25] offset0:192 offset1:196
	ds_write2_b64 v26, v[20:21], v[16:17] offset0:200 offset1:204
	v_mov_b32_e32 v16, v251
	v_pk_mul_f32 v[12:13], v[12:13], v[16:17] op_sel_hi:[1,0]
	v_pk_mul_f32 v[14:15], v[14:15], v[16:17] op_sel_hi:[1,0]
	v_cvt_pk_bf16_f32 v12, v12, v13
	v_cvt_pk_bf16_f32 v13, v14, v15
	ds_write_b64 v141, v[12:13] offset:59136
	s_and_saveexec_b64 s[44:45], s[12:13]
	s_cbranch_execz .LBB0_629
	v_add_co_u32_e32 v14, vcc, 0xfffdf000, v124
	s_nop 1
	v_addc_co_u32_e32 v15, vcc, -1, v125, vcc
	flat_store_dwordx2 v[14:15], v[12:13]
